# barrier one MFMA early with the trailing MFMA at priority 2 (enters the matrix pipe ahead of the partner's first MFMA); repeated lgkmcnt wait after the barrier dropped
# speedup vs baseline: 1.0010x; 1.0010x over previous
; #define PG8_STAGE(bufoff, gbase, voff) do { _Pragma("unroll") for (int _i = 0; _i < 2; ++_i) \
;         __builtin_amdgcn_global_load_lds((const unsigned*)((const char*)(gbase) + (voff)[_i]), (LAS unsigned*)(lds + (bufoff) + ldsw + _i * 8192), 16, 0, 0); } while (0)
; #define PG8_LDA(dst, b, h) do { _Pragma("unroll") for (int m = 0; m < 4; ++m) _Pragma("unroll") for (int k = 0; k < 2; ++k) dst[m][k] = *(const LAS bf16x8*)(lds + PG8_SA(b, h) + aoff + m * 2048 + k * 1024); } while (0)
; #define PG8_LDB(dst, b, h) do { _Pragma("unroll") for (int n = 0; n < 2; ++n) _Pragma("unroll") for (int k = 0; k < 2; ++k) dst[n][k] = *(const LAS bf16x8*)(lds + PG8_SB(b, h) + boff + n * 2048 + k * 1024); } while (0)
; #define PG8_MMA(ai, bj, At, Bt) do { __builtin_amdgcn_s_setprio(1); _Pragma("unroll") for (int m = 0; m < 4; ++m) _Pragma("unroll") for (int n = 0; n < 2; ++n) _Pragma("unroll") for (int k = 0; k < 2; ++k) \
;         acc[ai][bj][m][n] = __builtin_amdgcn_mfma_f32_16x16x32_bf16(Bt[n][k], At[m][k], acc[ai][bj][m][n], 0, 0, 0); __builtin_amdgcn_s_setprio(0); } while (0)
; #define PG8_WAIT_V(n) asm volatile("s_waitcnt vmcnt(" #n ")" ::: "memory")
; #define PG8_WAIT_L(n) asm volatile("s_waitcnt lgkmcnt(" #n ")" ::: "memory")
; #define PG8_BAR __builtin_amdgcn_s_barrier()
; #define PG8_SCHED __builtin_amdgcn_sched_barrier(0)
; template <class Epi, bool KREV = false>
; __device__ __forceinline__ void gemm_phase(LAS unsigned char* lds, const Gemm g, const StaticOrder& S, const Epi& E, int wave_s) {
;     ...
;             const bool last = (t == nt - 2);
;             const char* a1 = cA + (size_t)(t + 1) * kstep;
;             const char* a2 = last ? nA : cA + (size_t)(t + 2) * kstep; const char* b2 = last ? nB : cB + (size_t)(t + 2) * kstep;
;             const char* a3 = a2 + kstep; const char* b3 = b2 + kstep;
;             PG8_LDB(B0, 0, 0); PG8_LDB(B1, 0, 1); PG8_SCHED; PG8_LDA(At, 0, 0); PG8_STAGE(PG8_SA(1, 1), a1 + hstep, voffA);
;             PG8_WAIT_V(8); PG8_WAIT_L(0); PG8_BAR; PG8_MMA(0, 0, At, B0); PG8_MMA(0, 1, At, B1); PG8_BAR; PG8_SCHED;
;             PG8_LDA(At, 0, 1); PG8_STAGE(PG8_SB(0, 0), b2, voffB); PG8_STAGE(PG8_SB(0, 1), b2 + bh, voffB); PG8_STAGE(PG8_SA(0, 0), a2, voffA);
.LBB0_162:
	v_add_u32_e32 v138, 0x10000, v140
	ds_read_b128 v[146:149], v138
	ds_read_b128 v[150:153], v138 offset:1024
	ds_read_b128 v[154:157], v138 offset:2048
	ds_read_b128 v[158:161], v138 offset:3072
	v_add_u32_e32 v138, 0x14000, v140
	ds_read_b128 v[162:165], v138
	ds_read_b128 v[166:169], v138 offset:1024
	ds_read_b128 v[170:173], v138 offset:2048
	ds_read_b128 v[178:181], v138 offset:3072
	ds_read_b128 v[182:185], v143
	ds_read_b128 v[186:189], v143 offset:1024
	ds_read_b128 v[190:193], v143 offset:2048
	ds_read_b128 v[194:197], v143 offset:3072
	ds_read_b128 v[198:201], v143 offset:4096
	ds_read_b128 v[202:205], v143 offset:5120
	ds_read_b128 v[218:221], v143 offset:6144
	ds_read_b128 v[222:225], v143 offset:7168
	s_add_u32 s24, s22, 0xfff80080
	s_addc_u32 s25, s23, -1
	s_add_i32 s50, 0, 0x10000
	s_cmp_eq_u32 s49, 28
	s_cselect_b32 s27, s43, s25
	s_cselect_b32 s26, s44, s24
	s_cselect_b32 s25, s45, s48
	s_cselect_b32 s24, s46, s47
	s_add_i32 s52, 0, 0x14000
	s_add_i32 m0, s9, 0xc000
	s_nop 0
	global_load_lds_dwordx4 v134, s[22:23]
	s_add_i32 m0, s9, 0xe000
	s_nop 0
	global_load_lds_dwordx4 v136, s[22:23]
	s_waitcnt vmcnt(8)
	s_waitcnt lgkmcnt(0)
	s_barrier
	s_setprio 1
	v_mfma_f32_16x16x32_bf16 v[124:127], v[146:149], v[182:185], v[124:127]
	v_mfma_f32_16x16x32_bf16 v[120:123], v[154:157], v[182:185], v[120:123]
	v_mfma_f32_16x16x32_bf16 v[108:111], v[146:149], v[190:193], v[108:111]
	v_mfma_f32_16x16x32_bf16 v[104:107], v[154:157], v[190:193], v[104:107]
	v_mfma_f32_16x16x32_bf16 v[92:95], v[146:149], v[198:201], v[92:95]
	v_mfma_f32_16x16x32_bf16 v[88:91], v[154:157], v[198:201], v[88:91]
	v_mfma_f32_16x16x32_bf16 v[76:79], v[146:149], v[218:221], v[76:79]
	v_mfma_f32_16x16x32_bf16 v[72:75], v[154:157], v[218:221], v[72:75]
	v_mfma_f32_16x16x32_bf16 v[124:127], v[150:153], v[186:189], v[124:127]
	v_mfma_f32_16x16x32_bf16 v[120:123], v[158:161], v[186:189], v[120:123]
	v_mfma_f32_16x16x32_bf16 v[108:111], v[150:153], v[194:197], v[108:111]
	v_mfma_f32_16x16x32_bf16 v[104:107], v[158:161], v[194:197], v[104:107]
	v_mfma_f32_16x16x32_bf16 v[92:95], v[150:153], v[202:205], v[92:95]
	v_mfma_f32_16x16x32_bf16 v[88:91], v[158:161], v[202:205], v[88:91]
	v_mfma_f32_16x16x32_bf16 v[76:79], v[150:153], v[222:225], v[76:79]
	v_mfma_f32_16x16x32_bf16 v[72:75], v[158:161], v[222:225], v[72:75]
	s_setprio 0
	s_setprio 1
	v_mfma_f32_16x16x32_bf16 v[116:119], v[162:165], v[182:185], v[116:119]
	v_mfma_f32_16x16x32_bf16 v[112:115], v[170:173], v[182:185], v[112:115]
	v_mfma_f32_16x16x32_bf16 v[100:103], v[162:165], v[190:193], v[100:103]
	v_mfma_f32_16x16x32_bf16 v[96:99], v[170:173], v[190:193], v[96:99]
	v_mfma_f32_16x16x32_bf16 v[84:87], v[162:165], v[198:201], v[84:87]
	v_mfma_f32_16x16x32_bf16 v[80:83], v[170:173], v[198:201], v[80:83]
	v_mfma_f32_16x16x32_bf16 v[68:71], v[162:165], v[218:221], v[68:71]
	v_mfma_f32_16x16x32_bf16 v[64:67], v[170:173], v[218:221], v[64:67]
	v_mfma_f32_16x16x32_bf16 v[116:119], v[166:169], v[186:189], v[116:119]
	v_mfma_f32_16x16x32_bf16 v[112:115], v[178:181], v[186:189], v[112:115]
	v_mfma_f32_16x16x32_bf16 v[100:103], v[166:169], v[194:197], v[100:103]
	v_mfma_f32_16x16x32_bf16 v[96:99], v[178:181], v[194:197], v[96:99]
	v_mfma_f32_16x16x32_bf16 v[84:87], v[166:169], v[202:205], v[84:87]
	v_mfma_f32_16x16x32_bf16 v[80:83], v[178:181], v[202:205], v[80:83]
	v_mfma_f32_16x16x32_bf16 v[68:71], v[166:169], v[222:225], v[68:71]
	s_setprio 2
	s_barrier
	v_mfma_f32_16x16x32_bf16 v[64:67], v[178:181], v[222:225], v[64:67]
	s_setprio 0
	s_add_u32 s98, s24, s2
	s_addc_u32 s99, s25, s3
	s_add_u32 s100, s26, s2
	s_addc_u32 s101, s27, s3
	s_add_i32 s50, s50, s29
	s_mov_b32 m0, s50
	ds_read_b128 v[182:185], v143 offset:16384
	ds_read_b128 v[186:189], v143 offset:17408
	ds_read_b128 v[190:193], v143 offset:18432
	ds_read_b128 v[194:197], v143 offset:19456
	ds_read_b128 v[198:201], v143 offset:20480
	ds_read_b128 v[202:205], v143 offset:21504
	ds_read_b128 v[218:221], v143 offset:22528
	ds_read_b128 v[222:225], v143 offset:23552
	global_load_lds_dwordx4 v176, s[24:25]
	s_add_i32 m0, s50, 0x2000
	s_add_u32 s50, s24, 0x80000
	s_addc_u32 s51, s25, 0
	s_add_i32 s52, s52, s29
	global_load_lds_dwordx4 v132, s[24:25]
	s_mov_b32 m0, s52
	v_lshl_add_u64 v[226:227], s[26:27], 0, v[130:131]
	global_load_lds_dwordx4 v176, s[50:51]
	s_add_i32 m0, s52, 0x2000
	s_nop 0
	global_load_lds_dwordx4 v132, s[50:51]
	s_mov_b32 m0, s9
	s_nop 0
	global_load_lds_dwordx4 v128, s[26:27]
	s_mov_b32 m0, s11
	s_nop 0
	global_load_lds_dwordx4 v130, s[26:27]
	s_waitcnt vmcnt(8)
	s_waitcnt lgkmcnt(0)
	s_barrier
; #define PG8_STAGE(bufoff, gbase, voff) do { _Pragma("unroll") for (int _i = 0; _i < 2; ++_i) \
;         __builtin_amdgcn_global_load_lds((const unsigned*)((const char*)(gbase) + (voff)[_i]), (LAS unsigned*)(lds + (bufoff) + ldsw + _i * 8192), 16, 0, 0); } while (0)
; #define PG8_LDA(dst, b, h) do { _Pragma("unroll") for (int m = 0; m < 4; ++m) _Pragma("unroll") for (int k = 0; k < 2; ++k) dst[m][k] = *(const LAS bf16x8*)(lds + PG8_SA(b, h) + aoff + m * 2048 + k * 1024); } while (0)
; #define PG8_LDB(dst, b, h) do { _Pragma("unroll") for (int n = 0; n < 2; ++n) _Pragma("unroll") for (int k = 0; k < 2; ++k) dst[n][k] = *(const LAS bf16x8*)(lds + PG8_SB(b, h) + boff + n * 2048 + k * 1024); } while (0)
; #define PG8_MMA(ai, bj, At, Bt) do { __builtin_amdgcn_s_setprio(1); _Pragma("unroll") for (int m = 0; m < 4; ++m) _Pragma("unroll") for (int n = 0; n < 2; ++n) _Pragma("unroll") for (int k = 0; k < 2; ++k) \
;         acc[ai][bj][m][n] = __builtin_amdgcn_mfma_f32_16x16x32_bf16(Bt[n][k], At[m][k], acc[ai][bj][m][n], 0, 0, 0); __builtin_amdgcn_s_setprio(0); } while (0)
; #define PG8_WAIT_V(n) asm volatile("s_waitcnt vmcnt(" #n ")" ::: "memory")
; #define PG8_WAIT_L(n) asm volatile("s_waitcnt lgkmcnt(" #n ")" ::: "memory")
; #define PG8_BAR __builtin_amdgcn_s_barrier()
; #define PG8_SCHED __builtin_amdgcn_sched_barrier(0)
; template <class Epi, bool KREV = false>
; __device__ __forceinline__ void gemm_phase(LAS unsigned char* lds, const Gemm g, const StaticOrder& S, const Epi& E, int wave_s) {
;     ...
;             PG8_WAIT_V(8); PG8_WAIT_L(0); PG8_BAR; PG8_MMA(1, 0, At, B0); PG8_MMA(1, 1, At, B1); PG8_BAR; PG8_SCHED;
;             PG8_LDB(B0, 1, 0); PG8_LDB(B1, 1, 1); PG8_SCHED; PG8_LDA(At, 1, 0); PG8_STAGE(PG8_SA(0, 1), a2 + hstep, voffA);
;             PG8_WAIT_V(8); PG8_WAIT_L(0); PG8_BAR; PG8_MMA(0, 0, At, B0); PG8_MMA(0, 1, At, B1); PG8_BAR; PG8_SCHED;
	s_setprio 1
	v_mfma_f32_16x16x32_bf16 v[60:63], v[146:149], v[182:185], v[60:63]
	v_mfma_f32_16x16x32_bf16 v[56:59], v[154:157], v[182:185], v[56:59]
	v_mfma_f32_16x16x32_bf16 v[44:47], v[146:149], v[190:193], v[44:47]
	v_mfma_f32_16x16x32_bf16 v[40:43], v[154:157], v[190:193], v[40:43]
	v_mfma_f32_16x16x32_bf16 v[28:31], v[146:149], v[198:201], v[28:31]
	v_mfma_f32_16x16x32_bf16 v[24:27], v[154:157], v[198:201], v[24:27]
	v_mfma_f32_16x16x32_bf16 v[12:15], v[146:149], v[218:221], v[12:15]
	v_mfma_f32_16x16x32_bf16 v[8:11], v[154:157], v[218:221], v[8:11]
	v_mfma_f32_16x16x32_bf16 v[60:63], v[150:153], v[186:189], v[60:63]
	v_mfma_f32_16x16x32_bf16 v[56:59], v[158:161], v[186:189], v[56:59]
	v_mfma_f32_16x16x32_bf16 v[44:47], v[150:153], v[194:197], v[44:47]
	v_mfma_f32_16x16x32_bf16 v[40:43], v[158:161], v[194:197], v[40:43]
	v_mfma_f32_16x16x32_bf16 v[28:31], v[150:153], v[202:205], v[28:31]
	v_mfma_f32_16x16x32_bf16 v[24:27], v[158:161], v[202:205], v[24:27]
	v_mfma_f32_16x16x32_bf16 v[12:15], v[150:153], v[222:225], v[12:15]
	v_mfma_f32_16x16x32_bf16 v[8:11], v[158:161], v[222:225], v[8:11]
	s_setprio 0
	s_setprio 1
	v_mfma_f32_16x16x32_bf16 v[52:55], v[162:165], v[182:185], v[52:55]
	v_mfma_f32_16x16x32_bf16 v[48:51], v[170:173], v[182:185], v[48:51]
	v_mfma_f32_16x16x32_bf16 v[36:39], v[162:165], v[190:193], v[36:39]
	v_mfma_f32_16x16x32_bf16 v[32:35], v[170:173], v[190:193], v[32:35]
	v_mfma_f32_16x16x32_bf16 v[20:23], v[162:165], v[198:201], v[20:23]
	v_mfma_f32_16x16x32_bf16 v[16:19], v[170:173], v[198:201], v[16:19]
	v_mfma_f32_16x16x32_bf16 v[4:7], v[162:165], v[218:221], v[4:7]
	v_mfma_f32_16x16x32_bf16 v[0:3], v[170:173], v[218:221], v[0:3]
	v_mfma_f32_16x16x32_bf16 v[52:55], v[166:169], v[186:189], v[52:55]
	v_mfma_f32_16x16x32_bf16 v[48:51], v[178:181], v[186:189], v[48:51]
	v_mfma_f32_16x16x32_bf16 v[36:39], v[166:169], v[194:197], v[36:39]
	v_mfma_f32_16x16x32_bf16 v[32:35], v[178:181], v[194:197], v[32:35]
	v_mfma_f32_16x16x32_bf16 v[20:23], v[166:169], v[202:205], v[20:23]
	v_mfma_f32_16x16x32_bf16 v[16:19], v[178:181], v[202:205], v[16:19]
	v_mfma_f32_16x16x32_bf16 v[4:7], v[166:169], v[222:225], v[4:7]
	s_setprio 2
	s_barrier
	v_mfma_f32_16x16x32_bf16 v[0:3], v[178:181], v[222:225], v[0:3]
	s_setprio 0
	s_add_i32 s50, 0, 0x18000
	v_add_u32_e32 v145, s50, v140
	s_add_i32 s51, 0, 0x1c000
	ds_read_b128 v[146:149], v145
	ds_read_b128 v[150:153], v145 offset:1024
	ds_read_b128 v[154:157], v145 offset:2048
	ds_read_b128 v[158:161], v145 offset:3072
	v_add_u32_e32 v145, s51, v140
	ds_read_b128 v[162:165], v145
	ds_read_b128 v[166:169], v145 offset:1024
	ds_read_b128 v[170:173], v145 offset:2048
	ds_read_b128 v[178:181], v145 offset:3072
	s_add_u32 s26, s26, 0x80000
	s_addc_u32 s27, s27, 0
	s_mov_b32 m0, s36
	ds_read_b128 v[182:185], v143 offset:32768
	ds_read_b128 v[186:189], v143 offset:33792
	ds_read_b128 v[190:193], v143 offset:34816
	ds_read_b128 v[194:197], v143 offset:35840
	ds_read_b128 v[198:201], v143 offset:36864
	ds_read_b128 v[202:205], v143 offset:37888
	ds_read_b128 v[218:221], v143 offset:38912
	ds_read_b128 v[222:225], v143 offset:39936
	global_load_lds_dwordx4 v128, s[26:27]
	s_mov_b32 m0, s37
	s_nop 0
	global_load_lds_dwordx4 v130, s[26:27]
	s_waitcnt vmcnt(8)
	s_waitcnt lgkmcnt(0)
	s_barrier
	s_setprio 1
	v_mfma_f32_16x16x32_bf16 v[124:127], v[146:149], v[182:185], v[124:127]
	v_mfma_f32_16x16x32_bf16 v[120:123], v[154:157], v[182:185], v[120:123]
	v_mfma_f32_16x16x32_bf16 v[108:111], v[146:149], v[190:193], v[108:111]
	v_mfma_f32_16x16x32_bf16 v[104:107], v[154:157], v[190:193], v[104:107]
	v_mfma_f32_16x16x32_bf16 v[92:95], v[146:149], v[198:201], v[92:95]
	v_mfma_f32_16x16x32_bf16 v[88:91], v[154:157], v[198:201], v[88:91]
	v_mfma_f32_16x16x32_bf16 v[76:79], v[146:149], v[218:221], v[76:79]
	v_mfma_f32_16x16x32_bf16 v[72:75], v[154:157], v[218:221], v[72:75]
	v_mfma_f32_16x16x32_bf16 v[124:127], v[150:153], v[186:189], v[124:127]
	v_mfma_f32_16x16x32_bf16 v[120:123], v[158:161], v[186:189], v[120:123]
	v_mfma_f32_16x16x32_bf16 v[108:111], v[150:153], v[194:197], v[108:111]
	v_mfma_f32_16x16x32_bf16 v[104:107], v[158:161], v[194:197], v[104:107]
	v_mfma_f32_16x16x32_bf16 v[92:95], v[150:153], v[202:205], v[92:95]
	v_mfma_f32_16x16x32_bf16 v[88:91], v[158:161], v[202:205], v[88:91]
	v_mfma_f32_16x16x32_bf16 v[76:79], v[150:153], v[222:225], v[76:79]
	v_mfma_f32_16x16x32_bf16 v[72:75], v[158:161], v[222:225], v[72:75]
	s_setprio 0
	s_setprio 1
	v_mfma_f32_16x16x32_bf16 v[116:119], v[162:165], v[182:185], v[116:119]
	v_mfma_f32_16x16x32_bf16 v[112:115], v[170:173], v[182:185], v[112:115]
	v_mfma_f32_16x16x32_bf16 v[100:103], v[162:165], v[190:193], v[100:103]
	v_mfma_f32_16x16x32_bf16 v[96:99], v[170:173], v[190:193], v[96:99]
	v_mfma_f32_16x16x32_bf16 v[84:87], v[162:165], v[198:201], v[84:87]
	v_mfma_f32_16x16x32_bf16 v[80:83], v[170:173], v[198:201], v[80:83]
	v_mfma_f32_16x16x32_bf16 v[68:71], v[162:165], v[218:221], v[68:71]
	v_mfma_f32_16x16x32_bf16 v[64:67], v[170:173], v[218:221], v[64:67]
	v_mfma_f32_16x16x32_bf16 v[116:119], v[166:169], v[186:189], v[116:119]
	v_mfma_f32_16x16x32_bf16 v[112:115], v[178:181], v[186:189], v[112:115]
	v_mfma_f32_16x16x32_bf16 v[100:103], v[166:169], v[194:197], v[100:103]
	v_mfma_f32_16x16x32_bf16 v[96:99], v[178:181], v[194:197], v[96:99]
	v_mfma_f32_16x16x32_bf16 v[84:87], v[166:169], v[202:205], v[84:87]
	v_mfma_f32_16x16x32_bf16 v[80:83], v[178:181], v[202:205], v[80:83]
	v_mfma_f32_16x16x32_bf16 v[68:71], v[166:169], v[222:225], v[68:71]
	s_setprio 2
	s_barrier
; #define PG8_STAGE(bufoff, gbase, voff) do { _Pragma("unroll") for (int _i = 0; _i < 2; ++_i) \
;         __builtin_amdgcn_global_load_lds((const unsigned*)((const char*)(gbase) + (voff)[_i]), (LAS unsigned*)(lds + (bufoff) + ldsw + _i * 8192), 16, 0, 0); } while (0)
; #define PG8_LDA(dst, b, h) do { _Pragma("unroll") for (int m = 0; m < 4; ++m) _Pragma("unroll") for (int k = 0; k < 2; ++k) dst[m][k] = *(const LAS bf16x8*)(lds + PG8_SA(b, h) + aoff + m * 2048 + k * 1024); } while (0)
; #define PG8_MMA(ai, bj, At, Bt) do { __builtin_amdgcn_s_setprio(1); _Pragma("unroll") for (int m = 0; m < 4; ++m) _Pragma("unroll") for (int n = 0; n < 2; ++n) _Pragma("unroll") for (int k = 0; k < 2; ++k) \
;         acc[ai][bj][m][n] = __builtin_amdgcn_mfma_f32_16x16x32_bf16(Bt[n][k], At[m][k], acc[ai][bj][m][n], 0, 0, 0); __builtin_amdgcn_s_setprio(0); } while (0)
; #define PG8_WAIT_V(n) asm volatile("s_waitcnt vmcnt(" #n ")" ::: "memory")
; #define PG8_WAIT_L(n) asm volatile("s_waitcnt lgkmcnt(" #n ")" ::: "memory")
; #define PG8_BAR __builtin_amdgcn_s_barrier()
; #define PG8_SCHED __builtin_amdgcn_sched_barrier(0)
; template <class Epi, bool KREV = false>
; __device__ __forceinline__ void gemm_phase(LAS unsigned char* lds, const Gemm g, const StaticOrder& S, const Epi& E, int wave_s) {
;     ...
;             PG8_LDA(At, 1, 1); PG8_STAGE(PG8_SB(1, 0), b3, voffB); PG8_STAGE(PG8_SB(1, 1), b3 + bh, voffB); PG8_STAGE(PG8_SA(1, 0), a3, voffA);
;             PG8_WAIT_V(8); PG8_WAIT_L(0); PG8_BAR; PG8_MMA(1, 0, At, B0); PG8_MMA(1, 1, At, B1); PG8_BAR; PG8_SCHED;
	v_mfma_f32_16x16x32_bf16 v[64:67], v[178:181], v[222:225], v[64:67]
	s_setprio 0
	s_add_i32 s26, s50, s29
	s_mov_b32 m0, s26
	ds_read_b128 v[182:185], v143 offset:49152
	ds_read_b128 v[186:189], v143 offset:50176
	ds_read_b128 v[190:193], v143 offset:51200
	ds_read_b128 v[194:197], v143 offset:52224
	ds_read_b128 v[198:201], v143 offset:53248
	ds_read_b128 v[202:205], v143 offset:54272
	ds_read_b128 v[218:221], v143 offset:55296
	ds_read_b128 v[222:225], v143 offset:56320
	global_load_lds_dwordx4 v176, s[98:99]
	s_add_i32 m0, s26, 0x2000
	s_add_u32 s24, s24, 0x80080
	s_addc_u32 s25, s25, 0
	s_add_i32 s26, s51, s29
	global_load_lds_dwordx4 v132, s[98:99]
	s_mov_b32 m0, s26
	s_nop 0
	global_load_lds_dwordx4 v176, s[24:25]
	s_add_i32 m0, s26, 0x2000
	s_nop 0
	global_load_lds_dwordx4 v132, s[24:25]
	s_mov_b32 m0, s38
	s_nop 0
	global_load_lds_dwordx4 v128, s[100:101]
	v_lshl_add_u64 v[138:139], v[226:227], 0, s[2:3]
	s_mov_b32 m0, s39
	s_nop 0
	global_load_lds_dwordx4 v130, s[100:101]
	s_waitcnt vmcnt(8)
	s_waitcnt lgkmcnt(0)
	s_barrier
	s_setprio 1
	v_mfma_f32_16x16x32_bf16 v[60:63], v[146:149], v[182:185], v[60:63]
	v_mfma_f32_16x16x32_bf16 v[56:59], v[154:157], v[182:185], v[56:59]
	v_mfma_f32_16x16x32_bf16 v[44:47], v[146:149], v[190:193], v[44:47]
	v_mfma_f32_16x16x32_bf16 v[40:43], v[154:157], v[190:193], v[40:43]
	v_mfma_f32_16x16x32_bf16 v[28:31], v[146:149], v[198:201], v[28:31]
	v_mfma_f32_16x16x32_bf16 v[24:27], v[154:157], v[198:201], v[24:27]
	v_mfma_f32_16x16x32_bf16 v[12:15], v[146:149], v[218:221], v[12:15]
	v_mfma_f32_16x16x32_bf16 v[8:11], v[154:157], v[218:221], v[8:11]
	v_mfma_f32_16x16x32_bf16 v[60:63], v[150:153], v[186:189], v[60:63]
	v_mfma_f32_16x16x32_bf16 v[56:59], v[158:161], v[186:189], v[56:59]
	v_mfma_f32_16x16x32_bf16 v[44:47], v[150:153], v[194:197], v[44:47]
	v_mfma_f32_16x16x32_bf16 v[40:43], v[158:161], v[194:197], v[40:43]
	v_mfma_f32_16x16x32_bf16 v[28:31], v[150:153], v[202:205], v[28:31]
	v_mfma_f32_16x16x32_bf16 v[24:27], v[158:161], v[202:205], v[24:27]
	v_mfma_f32_16x16x32_bf16 v[12:15], v[150:153], v[222:225], v[12:15]
	v_mfma_f32_16x16x32_bf16 v[8:11], v[158:161], v[222:225], v[8:11]
	s_setprio 0
	s_setprio 1
	v_mfma_f32_16x16x32_bf16 v[52:55], v[162:165], v[182:185], v[52:55]
	v_mfma_f32_16x16x32_bf16 v[48:51], v[170:173], v[182:185], v[48:51]
	v_mfma_f32_16x16x32_bf16 v[36:39], v[162:165], v[190:193], v[36:39]
	v_mfma_f32_16x16x32_bf16 v[32:35], v[170:173], v[190:193], v[32:35]
	v_mfma_f32_16x16x32_bf16 v[20:23], v[162:165], v[198:201], v[20:23]
	v_mfma_f32_16x16x32_bf16 v[16:19], v[170:173], v[198:201], v[16:19]
	v_mfma_f32_16x16x32_bf16 v[4:7], v[162:165], v[218:221], v[4:7]
	v_mfma_f32_16x16x32_bf16 v[0:3], v[170:173], v[218:221], v[0:3]
	v_mfma_f32_16x16x32_bf16 v[52:55], v[166:169], v[186:189], v[52:55]
	v_mfma_f32_16x16x32_bf16 v[48:51], v[178:181], v[186:189], v[48:51]
	v_mfma_f32_16x16x32_bf16 v[36:39], v[166:169], v[194:197], v[36:39]
	v_mfma_f32_16x16x32_bf16 v[32:35], v[178:181], v[194:197], v[32:35]
	s_add_i32 s49, s49, 2
	s_add_u32 s22, s22, 0x100
	s_addc_u32 s23, s23, 0
	v_mfma_f32_16x16x32_bf16 v[20:23], v[166:169], v[202:205], v[20:23]
	s_add_u32 s47, s47, 0x100
	s_addc_u32 s48, s48, 0
	v_mfma_f32_16x16x32_bf16 v[16:19], v[178:181], v[202:205], v[16:19]
	s_cmp_gt_u32 s49, 29
	v_mfma_f32_16x16x32_bf16 v[4:7], v[166:169], v[222:225], v[4:7]
	s_setprio 2
	s_barrier
	v_mfma_f32_16x16x32_bf16 v[0:3], v[178:181], v[222:225], v[0:3]
	s_setprio 0
	s_cbranch_scc0 .LBB0_162
	s_and_b64 vcc, exec, s[18:19]
	s_cbranch_vccz .LBB0_165
	s_barrier

; #define PG8_STAGE(bufoff, gbase, voff) do { _Pragma("unroll") for (int _i = 0; _i < 2; ++_i) \
;         __builtin_amdgcn_global_load_lds((const unsigned*)((const char*)(gbase) + (voff)[_i]), (LAS unsigned*)(lds + (bufoff) + ldsw + _i * 8192), 16, 0, 0); } while (0)
; #define PG8_LDA(dst, b, h) do { _Pragma("unroll") for (int m = 0; m < 4; ++m) _Pragma("unroll") for (int k = 0; k < 2; ++k) dst[m][k] = *(const LAS bf16x8*)(lds + PG8_SA(b, h) + aoff + m * 2048 + k * 1024); } while (0)
; #define PG8_LDB(dst, b, h) do { _Pragma("unroll") for (int n = 0; n < 2; ++n) _Pragma("unroll") for (int k = 0; k < 2; ++k) dst[n][k] = *(const LAS bf16x8*)(lds + PG8_SB(b, h) + boff + n * 2048 + k * 1024); } while (0)
; #define PG8_MMA(ai, bj, At, Bt) do { __builtin_amdgcn_s_setprio(1); _Pragma("unroll") for (int m = 0; m < 4; ++m) _Pragma("unroll") for (int n = 0; n < 2; ++n) _Pragma("unroll") for (int k = 0; k < 2; ++k) \
;         acc[ai][bj][m][n] = __builtin_amdgcn_mfma_f32_16x16x32_bf16(Bt[n][k], At[m][k], acc[ai][bj][m][n], 0, 0, 0); __builtin_amdgcn_s_setprio(0); } while (0)
; #define PG8_WAIT_V(n) asm volatile("s_waitcnt vmcnt(" #n ")" ::: "memory")
; #define PG8_WAIT_L(n) asm volatile("s_waitcnt lgkmcnt(" #n ")" ::: "memory")
; #define PG8_BAR __builtin_amdgcn_s_barrier()
; #define PG8_SCHED __builtin_amdgcn_sched_barrier(0)
; template <class Epi, bool KREV = false>
; __device__ __forceinline__ void gemm_phase(LAS unsigned char* lds, const Gemm g, const StaticOrder& S, const Epi& E, int wave_s) {
;     ...
;             PG8_LDB(B0, 0, 0); PG8_LDB(B1, 0, 1); PG8_SCHED; PG8_LDA(At, 0, 0); PG8_STAGE(PG8_SA(1, 1), a1 + hstep, voffA);
;             PG8_WAIT_V(8); PG8_WAIT_L(0); PG8_BAR; PG8_MMA(0, 0, At, B0); PG8_MMA(0, 1, At, B1); PG8_BAR; PG8_SCHED;
;             PG8_LDA(At, 0, 1); PG8_STAGE(PG8_SB(0, 0), b2, voffB); PG8_STAGE(PG8_SB(0, 1), b2 + bh, voffB); PG8_STAGE(PG8_SA(0, 0), a2, voffA);
;             PG8_WAIT_V(8); PG8_WAIT_L(0); PG8_BAR; PG8_MMA(1, 0, At, B0); PG8_MMA(1, 1, At, B1); PG8_BAR; PG8_SCHED;
.LBB0_640:
	s_or_b32 s80, s9, 1
	s_lshl_b64 s[46:47], s[80:81], 7
	s_sub_u32 s27, 0, s46
	s_subb_u32 s45, 0, s47
	s_add_i32 s48, 0, 0x10000
	s_add_i32 s49, 0, 0x14000
	s_add_u32 s46, s41, s27
	s_addc_u32 s47, s42, s45
	s_add_i32 m0, s34, 0xc000
	s_nop 0
	global_load_lds_dwordx4 v156, s[46:47]
	s_add_i32 m0, s34, 0xe000
	s_nop 0
	global_load_lds_dwordx4 v154, s[46:47]
	s_waitcnt vmcnt(8)
	s_waitcnt lgkmcnt(0)
	s_barrier
	s_setprio 1
	v_mfma_f32_16x16x32_bf16 v[132:135], v[112:115], v[218:221], v[132:135]
	v_mfma_f32_16x16x32_bf16 v[120:123], v[136:139], v[218:221], v[120:123]
	v_mfma_f32_16x16x32_bf16 v[108:111], v[112:115], v[226:229], v[108:111]
	v_mfma_f32_16x16x32_bf16 v[104:107], v[136:139], v[226:229], v[104:107]
	v_mfma_f32_16x16x32_bf16 v[92:95], v[112:115], v[234:237], v[92:95]
	v_mfma_f32_16x16x32_bf16 v[88:91], v[136:139], v[234:237], v[88:91]
	v_mfma_f32_16x16x32_bf16 v[76:79], v[112:115], v[242:245], v[76:79]
	v_mfma_f32_16x16x32_bf16 v[72:75], v[136:139], v[242:245], v[72:75]
	v_mfma_f32_16x16x32_bf16 v[132:135], v[124:127], v[222:225], v[132:135]
	v_mfma_f32_16x16x32_bf16 v[120:123], v[140:143], v[222:225], v[120:123]
	v_mfma_f32_16x16x32_bf16 v[108:111], v[124:127], v[230:233], v[108:111]
	v_mfma_f32_16x16x32_bf16 v[104:107], v[140:143], v[230:233], v[104:107]
	v_mfma_f32_16x16x32_bf16 v[92:95], v[124:127], v[238:241], v[92:95]
	v_mfma_f32_16x16x32_bf16 v[88:91], v[140:143], v[238:241], v[88:91]
	v_mfma_f32_16x16x32_bf16 v[76:79], v[124:127], v[246:249], v[76:79]
	v_mfma_f32_16x16x32_bf16 v[72:75], v[140:143], v[246:249], v[72:75]
	s_setprio 0
	s_setprio 1
	v_mfma_f32_16x16x32_bf16 v[128:131], v[144:147], v[218:221], v[128:131]
	v_mfma_f32_16x16x32_bf16 v[116:119], v[194:197], v[218:221], v[116:119]
	v_mfma_f32_16x16x32_bf16 v[100:103], v[144:147], v[226:229], v[100:103]
	v_mfma_f32_16x16x32_bf16 v[96:99], v[194:197], v[226:229], v[96:99]
	v_mfma_f32_16x16x32_bf16 v[84:87], v[144:147], v[234:237], v[84:87]
	v_mfma_f32_16x16x32_bf16 v[80:83], v[194:197], v[234:237], v[80:83]
	v_mfma_f32_16x16x32_bf16 v[68:71], v[144:147], v[242:245], v[68:71]
	v_mfma_f32_16x16x32_bf16 v[64:67], v[194:197], v[242:245], v[64:67]
	v_mfma_f32_16x16x32_bf16 v[128:131], v[148:151], v[222:225], v[128:131]
	v_mfma_f32_16x16x32_bf16 v[116:119], v[202:205], v[222:225], v[116:119]
	v_mfma_f32_16x16x32_bf16 v[100:103], v[148:151], v[230:233], v[100:103]
	v_mfma_f32_16x16x32_bf16 v[96:99], v[202:205], v[230:233], v[96:99]
	v_mfma_f32_16x16x32_bf16 v[84:87], v[148:151], v[238:241], v[84:87]
	v_mfma_f32_16x16x32_bf16 v[80:83], v[202:205], v[238:241], v[80:83]
	v_mfma_f32_16x16x32_bf16 v[68:71], v[148:151], v[246:249], v[68:71]
	s_setprio 2
	s_barrier
	v_mfma_f32_16x16x32_bf16 v[64:67], v[202:205], v[246:249], v[64:67]
	s_setprio 0
	s_add_u32 s98, s28, s78
	s_addc_u32 s99, s29, s79
	s_add_u32 s100, s30, s78
	s_addc_u32 s101, s31, s79
	s_add_i32 s27, s48, s1
	s_mov_b32 m0, s27
	ds_read_b128 v[218:221], v201 offset:16384
	ds_read_b128 v[222:225], v201 offset:17408
	ds_read_b128 v[226:229], v201 offset:18432
	ds_read_b128 v[230:233], v201 offset:19456
	ds_read_b128 v[234:237], v201 offset:20480
	ds_read_b128 v[238:241], v201 offset:21504
	ds_read_b128 v[242:245], v201 offset:22528
	ds_read_b128 v[246:249], v201 offset:23552
	global_load_lds_dwordx4 v176, s[28:29]
	s_add_i32 m0, s27, 0x2000
	s_add_u32 s46, s28, 0x80000
	s_addc_u32 s47, s29, 0
	s_add_i32 s27, s49, s1
	global_load_lds_dwordx4 v152, s[28:29]
	s_mov_b32 m0, s27
	s_nop 0
	global_load_lds_dwordx4 v176, s[46:47]
	s_add_i32 m0, s27, 0x2000
	s_nop 0
	global_load_lds_dwordx4 v152, s[46:47]
	s_mov_b32 m0, s34
	s_nop 0
	global_load_lds_dwordx4 v156, s[30:31]
	s_mov_b32 m0, s35
	s_nop 0
	global_load_lds_dwordx4 v154, s[30:31]
	s_waitcnt vmcnt(8)
	s_waitcnt lgkmcnt(0)
	s_barrier
	s_setprio 1
	v_mfma_f32_16x16x32_bf16 v[60:63], v[112:115], v[218:221], v[60:63]
	v_mfma_f32_16x16x32_bf16 v[56:59], v[136:139], v[218:221], v[56:59]
	v_mfma_f32_16x16x32_bf16 v[44:47], v[112:115], v[226:229], v[44:47]
	v_mfma_f32_16x16x32_bf16 v[40:43], v[136:139], v[226:229], v[40:43]
	v_mfma_f32_16x16x32_bf16 v[28:31], v[112:115], v[234:237], v[28:31]
	v_mfma_f32_16x16x32_bf16 v[24:27], v[136:139], v[234:237], v[24:27]
	v_mfma_f32_16x16x32_bf16 v[12:15], v[112:115], v[242:245], v[12:15]
	v_mfma_f32_16x16x32_bf16 v[8:11], v[136:139], v[242:245], v[8:11]
	v_mfma_f32_16x16x32_bf16 v[60:63], v[124:127], v[222:225], v[60:63]
	v_mfma_f32_16x16x32_bf16 v[56:59], v[140:143], v[222:225], v[56:59]
	v_mfma_f32_16x16x32_bf16 v[44:47], v[124:127], v[230:233], v[44:47]
	v_mfma_f32_16x16x32_bf16 v[40:43], v[140:143], v[230:233], v[40:43]
	v_mfma_f32_16x16x32_bf16 v[28:31], v[124:127], v[238:241], v[28:31]
	v_mfma_f32_16x16x32_bf16 v[24:27], v[140:143], v[238:241], v[24:27]
	v_mfma_f32_16x16x32_bf16 v[12:15], v[124:127], v[246:249], v[12:15]
	v_mfma_f32_16x16x32_bf16 v[8:11], v[140:143], v[246:249], v[8:11]
	s_setprio 0
	s_setprio 1
	v_mfma_f32_16x16x32_bf16 v[52:55], v[144:147], v[218:221], v[52:55]
	v_mfma_f32_16x16x32_bf16 v[48:51], v[194:197], v[218:221], v[48:51]
	v_mfma_f32_16x16x32_bf16 v[36:39], v[144:147], v[226:229], v[36:39]
	v_mfma_f32_16x16x32_bf16 v[32:35], v[194:197], v[226:229], v[32:35]
	v_mfma_f32_16x16x32_bf16 v[20:23], v[144:147], v[234:237], v[20:23]
	v_mfma_f32_16x16x32_bf16 v[16:19], v[194:197], v[234:237], v[16:19]
	v_mfma_f32_16x16x32_bf16 v[4:7], v[144:147], v[242:245], v[4:7]
	v_mfma_f32_16x16x32_bf16 v[0:3], v[194:197], v[242:245], v[0:3]
	v_mfma_f32_16x16x32_bf16 v[52:55], v[148:151], v[222:225], v[52:55]
	v_mfma_f32_16x16x32_bf16 v[48:51], v[202:205], v[222:225], v[48:51]
	v_mfma_f32_16x16x32_bf16 v[36:39], v[148:151], v[230:233], v[36:39]
	v_mfma_f32_16x16x32_bf16 v[32:35], v[202:205], v[230:233], v[32:35]
	v_mfma_f32_16x16x32_bf16 v[20:23], v[148:151], v[238:241], v[20:23]
	v_mfma_f32_16x16x32_bf16 v[16:19], v[202:205], v[238:241], v[16:19]
	v_mfma_f32_16x16x32_bf16 v[4:7], v[148:151], v[246:249], v[4:7]
	s_setprio 2
	s_barrier
; #define PG8_STAGE(bufoff, gbase, voff) do { _Pragma("unroll") for (int _i = 0; _i < 2; ++_i) \
;         __builtin_amdgcn_global_load_lds((const unsigned*)((const char*)(gbase) + (voff)[_i]), (LAS unsigned*)(lds + (bufoff) + ldsw + _i * 8192), 16, 0, 0); } while (0)
; #define PG8_LDA(dst, b, h) do { _Pragma("unroll") for (int m = 0; m < 4; ++m) _Pragma("unroll") for (int k = 0; k < 2; ++k) dst[m][k] = *(const LAS bf16x8*)(lds + PG8_SA(b, h) + aoff + m * 2048 + k * 1024); } while (0)
; #define PG8_LDB(dst, b, h) do { _Pragma("unroll") for (int n = 0; n < 2; ++n) _Pragma("unroll") for (int k = 0; k < 2; ++k) dst[n][k] = *(const LAS bf16x8*)(lds + PG8_SB(b, h) + boff + n * 2048 + k * 1024); } while (0)
; #define PG8_MMA(ai, bj, At, Bt) do { __builtin_amdgcn_s_setprio(1); _Pragma("unroll") for (int m = 0; m < 4; ++m) _Pragma("unroll") for (int n = 0; n < 2; ++n) _Pragma("unroll") for (int k = 0; k < 2; ++k) \
;         acc[ai][bj][m][n] = __builtin_amdgcn_mfma_f32_16x16x32_bf16(Bt[n][k], At[m][k], acc[ai][bj][m][n], 0, 0, 0); __builtin_amdgcn_s_setprio(0); } while (0)
; #define PG8_WAIT_V(n) asm volatile("s_waitcnt vmcnt(" #n ")" ::: "memory")
; #define PG8_WAIT_L(n) asm volatile("s_waitcnt lgkmcnt(" #n ")" ::: "memory")
; #define PG8_BAR __builtin_amdgcn_s_barrier()
; #define PG8_SCHED __builtin_amdgcn_sched_barrier(0)
; template <class Epi, bool KREV = false>
; __device__ __forceinline__ void gemm_phase(LAS unsigned char* lds, const Gemm g, const StaticOrder& S, const Epi& E, int wave_s) {
;     ...
;             PG8_LDB(B0, 1, 0); PG8_LDB(B1, 1, 1); PG8_SCHED; PG8_LDA(At, 1, 0); PG8_STAGE(PG8_SA(0, 1), a2 + hstep, voffA);
;             PG8_WAIT_V(8); PG8_WAIT_L(0); PG8_BAR; PG8_MMA(0, 0, At, B0); PG8_MMA(0, 1, At, B1); PG8_BAR; PG8_SCHED;
;             PG8_LDA(At, 1, 1); PG8_STAGE(PG8_SB(1, 0), b3, voffB); PG8_STAGE(PG8_SB(1, 1), b3 + bh, voffB); PG8_STAGE(PG8_SA(1, 0), a3, voffA);
;             PG8_WAIT_V(8); PG8_WAIT_L(0); PG8_BAR; PG8_MMA(1, 0, At, B0); PG8_MMA(1, 1, At, B1); PG8_BAR; PG8_SCHED;
	v_mfma_f32_16x16x32_bf16 v[0:3], v[202:205], v[246:249], v[0:3]
	s_setprio 0
	s_add_i32 s27, 0, 0x18000
	s_add_i32 s45, 0, 0x1c000
	v_add_u32_e32 v140, s27, v199
	v_add_u32_e32 v202, s45, v199
	ds_read_b128 v[112:115], v140
	ds_read_b128 v[124:127], v140 offset:1024
	ds_read_b128 v[136:139], v140 offset:2048
	ds_read_b128 v[140:143], v140 offset:3072
	ds_read_b128 v[144:147], v202
	ds_read_b128 v[148:151], v202 offset:1024
	ds_read_b128 v[194:197], v202 offset:2048
	ds_read_b128 v[202:205], v202 offset:3072
	s_add_u32 s30, s30, 0x80000
	s_addc_u32 s31, s31, 0
	s_mov_b32 m0, s36
	ds_read_b128 v[218:221], v201 offset:32768
	ds_read_b128 v[222:225], v201 offset:33792
	ds_read_b128 v[226:229], v201 offset:34816
	ds_read_b128 v[230:233], v201 offset:35840
	ds_read_b128 v[234:237], v201 offset:36864
	ds_read_b128 v[238:241], v201 offset:37888
	ds_read_b128 v[242:245], v201 offset:38912
	ds_read_b128 v[246:249], v201 offset:39936
	global_load_lds_dwordx4 v156, s[30:31]
	s_mov_b32 m0, s37
	s_nop 0
	global_load_lds_dwordx4 v154, s[30:31]
	s_waitcnt vmcnt(8)
	s_waitcnt lgkmcnt(0)
	s_barrier
	s_setprio 1
	v_mfma_f32_16x16x32_bf16 v[132:135], v[112:115], v[218:221], v[132:135]
	v_mfma_f32_16x16x32_bf16 v[120:123], v[136:139], v[218:221], v[120:123]
	v_mfma_f32_16x16x32_bf16 v[108:111], v[112:115], v[226:229], v[108:111]
	v_mfma_f32_16x16x32_bf16 v[104:107], v[136:139], v[226:229], v[104:107]
	v_mfma_f32_16x16x32_bf16 v[92:95], v[112:115], v[234:237], v[92:95]
	v_mfma_f32_16x16x32_bf16 v[88:91], v[136:139], v[234:237], v[88:91]
	v_mfma_f32_16x16x32_bf16 v[76:79], v[112:115], v[242:245], v[76:79]
	v_mfma_f32_16x16x32_bf16 v[72:75], v[136:139], v[242:245], v[72:75]
	v_mfma_f32_16x16x32_bf16 v[132:135], v[124:127], v[222:225], v[132:135]
	v_mfma_f32_16x16x32_bf16 v[120:123], v[140:143], v[222:225], v[120:123]
	v_mfma_f32_16x16x32_bf16 v[108:111], v[124:127], v[230:233], v[108:111]
	v_mfma_f32_16x16x32_bf16 v[104:107], v[140:143], v[230:233], v[104:107]
	v_mfma_f32_16x16x32_bf16 v[92:95], v[124:127], v[238:241], v[92:95]
	v_mfma_f32_16x16x32_bf16 v[88:91], v[140:143], v[238:241], v[88:91]
	v_mfma_f32_16x16x32_bf16 v[76:79], v[124:127], v[246:249], v[76:79]
	v_mfma_f32_16x16x32_bf16 v[72:75], v[140:143], v[246:249], v[72:75]
	s_setprio 0
	s_setprio 1
	v_mfma_f32_16x16x32_bf16 v[128:131], v[144:147], v[218:221], v[128:131]
	v_mfma_f32_16x16x32_bf16 v[116:119], v[194:197], v[218:221], v[116:119]
	v_mfma_f32_16x16x32_bf16 v[100:103], v[144:147], v[226:229], v[100:103]
	v_mfma_f32_16x16x32_bf16 v[96:99], v[194:197], v[226:229], v[96:99]
	v_mfma_f32_16x16x32_bf16 v[84:87], v[144:147], v[234:237], v[84:87]
	v_mfma_f32_16x16x32_bf16 v[80:83], v[194:197], v[234:237], v[80:83]
	v_mfma_f32_16x16x32_bf16 v[68:71], v[144:147], v[242:245], v[68:71]
	v_mfma_f32_16x16x32_bf16 v[64:67], v[194:197], v[242:245], v[64:67]
	v_mfma_f32_16x16x32_bf16 v[128:131], v[148:151], v[222:225], v[128:131]
	v_mfma_f32_16x16x32_bf16 v[116:119], v[202:205], v[222:225], v[116:119]
	v_mfma_f32_16x16x32_bf16 v[100:103], v[148:151], v[230:233], v[100:103]
	v_mfma_f32_16x16x32_bf16 v[96:99], v[202:205], v[230:233], v[96:99]
	v_mfma_f32_16x16x32_bf16 v[84:87], v[148:151], v[238:241], v[84:87]
	v_mfma_f32_16x16x32_bf16 v[80:83], v[202:205], v[238:241], v[80:83]
	v_mfma_f32_16x16x32_bf16 v[68:71], v[148:151], v[246:249], v[68:71]
	s_setprio 2
	s_barrier
	v_mfma_f32_16x16x32_bf16 v[64:67], v[202:205], v[246:249], v[64:67]
	s_setprio 0
	s_add_i32 s27, s27, s1
	s_mov_b32 m0, s27
	ds_read_b128 v[218:221], v201 offset:49152
	ds_read_b128 v[222:225], v201 offset:50176
	ds_read_b128 v[226:229], v201 offset:51200
	ds_read_b128 v[230:233], v201 offset:52224
	ds_read_b128 v[234:237], v201 offset:53248
	ds_read_b128 v[238:241], v201 offset:54272
	ds_read_b128 v[242:245], v201 offset:55296
	ds_read_b128 v[246:249], v201 offset:56320
	global_load_lds_dwordx4 v176, s[98:99]
	s_add_i32 m0, s27, 0x2000
	s_add_u32 s28, s28, 0x7ff80
	s_addc_u32 s29, s29, 0
	s_add_i32 s27, s45, s1
	global_load_lds_dwordx4 v152, s[98:99]
	s_mov_b32 m0, s27
	s_nop 0
	global_load_lds_dwordx4 v176, s[28:29]
	s_add_i32 m0, s27, 0x2000
	s_nop 0
	global_load_lds_dwordx4 v152, s[28:29]
	s_mov_b32 m0, s39
	s_nop 0
	global_load_lds_dwordx4 v156, s[100:101]
	s_mov_b32 m0, s40
	s_nop 0
	global_load_lds_dwordx4 v154, s[100:101]
	s_waitcnt vmcnt(8)
	s_waitcnt lgkmcnt(0)
	s_barrier
	s_setprio 1
	v_mfma_f32_16x16x32_bf16 v[60:63], v[112:115], v[218:221], v[60:63]
	v_mfma_f32_16x16x32_bf16 v[56:59], v[136:139], v[218:221], v[56:59]
	v_mfma_f32_16x16x32_bf16 v[44:47], v[112:115], v[226:229], v[44:47]
	v_mfma_f32_16x16x32_bf16 v[40:43], v[136:139], v[226:229], v[40:43]
	v_mfma_f32_16x16x32_bf16 v[28:31], v[112:115], v[234:237], v[28:31]
	v_mfma_f32_16x16x32_bf16 v[24:27], v[136:139], v[234:237], v[24:27]
	v_mfma_f32_16x16x32_bf16 v[12:15], v[112:115], v[242:245], v[12:15]
	v_mfma_f32_16x16x32_bf16 v[8:11], v[136:139], v[242:245], v[8:11]
	v_mfma_f32_16x16x32_bf16 v[60:63], v[124:127], v[222:225], v[60:63]
	v_mfma_f32_16x16x32_bf16 v[56:59], v[140:143], v[222:225], v[56:59]
	v_mfma_f32_16x16x32_bf16 v[44:47], v[124:127], v[230:233], v[44:47]
	v_mfma_f32_16x16x32_bf16 v[40:43], v[140:143], v[230:233], v[40:43]
	v_mfma_f32_16x16x32_bf16 v[28:31], v[124:127], v[238:241], v[28:31]
	v_mfma_f32_16x16x32_bf16 v[24:27], v[140:143], v[238:241], v[24:27]
	v_mfma_f32_16x16x32_bf16 v[12:15], v[124:127], v[246:249], v[12:15]
	v_mfma_f32_16x16x32_bf16 v[8:11], v[140:143], v[246:249], v[8:11]
	s_setprio 0
	s_setprio 1
	v_mfma_f32_16x16x32_bf16 v[52:55], v[144:147], v[218:221], v[52:55]
	v_mfma_f32_16x16x32_bf16 v[48:51], v[194:197], v[218:221], v[48:51]
	v_mfma_f32_16x16x32_bf16 v[36:39], v[144:147], v[226:229], v[36:39]
	v_mfma_f32_16x16x32_bf16 v[32:35], v[194:197], v[226:229], v[32:35]
	v_mfma_f32_16x16x32_bf16 v[20:23], v[144:147], v[234:237], v[20:23]
	v_mfma_f32_16x16x32_bf16 v[16:19], v[194:197], v[234:237], v[16:19]
	v_mfma_f32_16x16x32_bf16 v[4:7], v[144:147], v[242:245], v[4:7]
	v_mfma_f32_16x16x32_bf16 v[0:3], v[194:197], v[242:245], v[0:3]
	v_mfma_f32_16x16x32_bf16 v[52:55], v[148:151], v[222:225], v[52:55]
	v_mfma_f32_16x16x32_bf16 v[48:51], v[202:205], v[222:225], v[48:51]
	v_mfma_f32_16x16x32_bf16 v[36:39], v[148:151], v[230:233], v[36:39]
	v_mfma_f32_16x16x32_bf16 v[32:35], v[202:205], v[230:233], v[32:35]
	s_cmp_gt_u32 s9, 29
	s_mov_b32 s9, s26
	v_mfma_f32_16x16x32_bf16 v[20:23], v[148:151], v[238:241], v[20:23]
	v_mfma_f32_16x16x32_bf16 v[16:19], v[202:205], v[238:241], v[16:19]
	v_mfma_f32_16x16x32_bf16 v[4:7], v[148:151], v[246:249], v[4:7]
	s_setprio 2
	s_barrier
	v_mfma_f32_16x16x32_bf16 v[0:3], v[202:205], v[246:249], v[0:3]
	s_setprio 0
	s_cbranch_scc1 .LBB0_645

; #define PG8_STAGE(bufoff, gbase, voff) do { _Pragma("unroll") for (int _i = 0; _i < 2; ++_i) \
;         __builtin_amdgcn_global_load_lds((const unsigned*)((const char*)(gbase) + (voff)[_i]), (LAS unsigned*)(lds + (bufoff) + ldsw + _i * 8192), 16, 0, 0); } while (0)
; #define PG8_LDA(dst, b, h) do { _Pragma("unroll") for (int m = 0; m < 4; ++m) _Pragma("unroll") for (int k = 0; k < 2; ++k) dst[m][k] = *(const LAS bf16x8*)(lds + PG8_SA(b, h) + aoff + m * 2048 + k * 1024); } while (0)
; #define PG8_LDB(dst, b, h) do { _Pragma("unroll") for (int n = 0; n < 2; ++n) _Pragma("unroll") for (int k = 0; k < 2; ++k) dst[n][k] = *(const LAS bf16x8*)(lds + PG8_SB(b, h) + boff + n * 2048 + k * 1024); } while (0)
; #define PG8_MMA(ai, bj, At, Bt) do { __builtin_amdgcn_s_setprio(1); _Pragma("unroll") for (int m = 0; m < 4; ++m) _Pragma("unroll") for (int n = 0; n < 2; ++n) _Pragma("unroll") for (int k = 0; k < 2; ++k) \
;         acc[ai][bj][m][n] = __builtin_amdgcn_mfma_f32_16x16x32_bf16(Bt[n][k], At[m][k], acc[ai][bj][m][n], 0, 0, 0); __builtin_amdgcn_s_setprio(0); } while (0)
; #define PG8_WAIT_V(n) asm volatile("s_waitcnt vmcnt(" #n ")" ::: "memory")
; #define PG8_WAIT_L(n) asm volatile("s_waitcnt lgkmcnt(" #n ")" ::: "memory")
; #define PG8_BAR __builtin_amdgcn_s_barrier()
; #define PG8_SCHED __builtin_amdgcn_sched_barrier(0)
; template <class Epi, bool KREV = false>
; __device__ __forceinline__ void gemm_phase(LAS unsigned char* lds, const Gemm g, const StaticOrder& S, const Epi& E, int wave_s) {
;     ...
;             const bool last = (t == nt - 2);
;             const char* a1 = cA + (size_t)(t + 1) * kstep;
;             const char* a2 = last ? nA : cA + (size_t)(t + 2) * kstep; const char* b2 = last ? nB : cB + (size_t)(t + 2) * kstep;
;             const char* a3 = a2 + kstep; const char* b3 = b2 + kstep;
;             PG8_LDB(B0, 0, 0); PG8_LDB(B1, 0, 1); PG8_SCHED; PG8_LDA(At, 0, 0); PG8_STAGE(PG8_SA(1, 1), a1 + hstep, voffA);
;             PG8_WAIT_V(8); PG8_WAIT_L(0); PG8_BAR; PG8_MMA(0, 0, At, B0); PG8_MMA(0, 1, At, B1); PG8_BAR; PG8_SCHED;
;             PG8_LDA(At, 0, 1); PG8_STAGE(PG8_SB(0, 0), b2, voffB); PG8_STAGE(PG8_SB(0, 1), b2 + bh, voffB); PG8_STAGE(PG8_SA(0, 0), a2, voffA);
;             PG8_WAIT_V(8); PG8_WAIT_L(0); PG8_BAR; PG8_MMA(1, 0, At, B0); PG8_MMA(1, 1, At, B1); PG8_BAR; PG8_SCHED;
.LBB0_836:
	v_add_u32_e32 v154, 0x10000, v135
	v_add_u32_e32 v170, 0x14000, v135
	ds_read_b128 v[142:145], v154
	ds_read_b128 v[146:149], v154 offset:1024
	ds_read_b128 v[150:153], v154 offset:2048
	ds_read_b128 v[154:157], v154 offset:3072
	ds_read_b128 v[158:161], v170
	ds_read_b128 v[162:165], v170 offset:1024
	ds_read_b128 v[166:169], v170 offset:2048
	ds_read_b128 v[170:173], v170 offset:3072
	ds_read_b128 v[178:181], v194
	ds_read_b128 v[182:185], v194 offset:1024
	ds_read_b128 v[186:189], v194 offset:2048
	ds_read_b128 v[196:199], v194 offset:3072
	ds_read_b128 v[200:203], v194 offset:4096
	ds_read_b128 v[204:207], v194 offset:5120
	ds_read_b128 v[218:221], v194 offset:6144
	ds_read_b128 v[222:225], v194 offset:7168
	s_add_u32 s56, s54, 0xfff80080
	s_addc_u32 s57, s55, -1
	s_add_i32 s84, 0, 0x10000
	s_cmp_eq_u32 s83, 28
	s_cselect_b32 s59, s73, s57
	s_cselect_b32 s58, s74, s56
	s_cselect_b32 s57, s75, s82
	s_cselect_b32 s56, s77, s80
	s_add_i32 s86, 0, 0x14000
	s_add_i32 m0, s19, 0xc000
	s_nop 0
	global_load_lds_dwordx4 v138, s[54:55]
	s_add_i32 m0, s19, 0xe000
	s_nop 0
	global_load_lds_dwordx4 v140, s[54:55]
	s_waitcnt vmcnt(8)
	s_waitcnt lgkmcnt(0)
	s_barrier
	s_setprio 1
	v_mfma_f32_16x16x32_bf16 v[124:127], v[142:145], v[178:181], v[124:127]
	v_mfma_f32_16x16x32_bf16 v[120:123], v[150:153], v[178:181], v[120:123]
	v_mfma_f32_16x16x32_bf16 v[68:71], v[142:145], v[186:189], v[68:71]
	v_mfma_f32_16x16x32_bf16 v[64:67], v[150:153], v[186:189], v[64:67]
	v_mfma_f32_16x16x32_bf16 v[60:63], v[142:145], v[200:203], v[60:63]
	v_mfma_f32_16x16x32_bf16 v[20:23], v[150:153], v[200:203], v[20:23]
	v_mfma_f32_16x16x32_bf16 v[108:111], v[142:145], v[218:221], v[108:111]
	v_mfma_f32_16x16x32_bf16 v[104:107], v[150:153], v[218:221], v[104:107]
	v_mfma_f32_16x16x32_bf16 v[124:127], v[146:149], v[182:185], v[124:127]
	v_mfma_f32_16x16x32_bf16 v[120:123], v[154:157], v[182:185], v[120:123]
	v_mfma_f32_16x16x32_bf16 v[68:71], v[146:149], v[196:199], v[68:71]
	v_mfma_f32_16x16x32_bf16 v[64:67], v[154:157], v[196:199], v[64:67]
	v_mfma_f32_16x16x32_bf16 v[60:63], v[146:149], v[204:207], v[60:63]
	v_mfma_f32_16x16x32_bf16 v[20:23], v[154:157], v[204:207], v[20:23]
	v_mfma_f32_16x16x32_bf16 v[108:111], v[146:149], v[222:225], v[108:111]
	v_mfma_f32_16x16x32_bf16 v[104:107], v[154:157], v[222:225], v[104:107]
	s_setprio 0
	s_setprio 1
	v_mfma_f32_16x16x32_bf16 v[116:119], v[158:161], v[178:181], v[116:119]
	v_mfma_f32_16x16x32_bf16 v[112:115], v[166:169], v[178:181], v[112:115]
	v_mfma_f32_16x16x32_bf16 v[52:55], v[158:161], v[186:189], v[52:55]
	v_mfma_f32_16x16x32_bf16 v[48:51], v[166:169], v[186:189], v[48:51]
	v_mfma_f32_16x16x32_bf16 v[44:47], v[158:161], v[200:203], v[44:47]
	v_mfma_f32_16x16x32_bf16 v[16:19], v[166:169], v[200:203], v[16:19]
	v_mfma_f32_16x16x32_bf16 v[100:103], v[158:161], v[218:221], v[100:103]
	v_mfma_f32_16x16x32_bf16 v[96:99], v[166:169], v[218:221], v[96:99]
	v_mfma_f32_16x16x32_bf16 v[116:119], v[162:165], v[182:185], v[116:119]
	v_mfma_f32_16x16x32_bf16 v[112:115], v[170:173], v[182:185], v[112:115]
	v_mfma_f32_16x16x32_bf16 v[52:55], v[162:165], v[196:199], v[52:55]
	v_mfma_f32_16x16x32_bf16 v[48:51], v[170:173], v[196:199], v[48:51]
	v_mfma_f32_16x16x32_bf16 v[44:47], v[162:165], v[204:207], v[44:47]
	v_mfma_f32_16x16x32_bf16 v[16:19], v[170:173], v[204:207], v[16:19]
	v_mfma_f32_16x16x32_bf16 v[100:103], v[162:165], v[222:225], v[100:103]
	s_setprio 2
	s_barrier
	v_mfma_f32_16x16x32_bf16 v[96:99], v[170:173], v[222:225], v[96:99]
	s_setprio 0
	s_add_u32 s98, s56, s2
	s_addc_u32 s99, s57, s3
	s_add_u32 s100, s58, s2
	s_addc_u32 s101, s59, s3
	s_add_i32 s84, s84, s66
	s_mov_b32 m0, s84
	ds_read_b128 v[178:181], v194 offset:16384
	ds_read_b128 v[182:185], v194 offset:17408
	ds_read_b128 v[186:189], v194 offset:18432
	ds_read_b128 v[196:199], v194 offset:19456
	ds_read_b128 v[200:203], v194 offset:20480
	ds_read_b128 v[204:207], v194 offset:21504
	ds_read_b128 v[218:221], v194 offset:22528
	ds_read_b128 v[222:225], v194 offset:23552
	global_load_lds_dwordx4 v176, s[56:57]
	s_add_i32 m0, s84, 0x2000
	s_add_u32 s84, s56, 0x1600000
	s_addc_u32 s85, s57, 0
	s_add_i32 s86, s86, s66
	global_load_lds_dwordx4 v132, s[56:57]
	s_mov_b32 m0, s86
	s_nop 0
	global_load_lds_dwordx4 v176, s[84:85]
	s_add_i32 m0, s86, 0x2000
	s_nop 0
	global_load_lds_dwordx4 v132, s[84:85]
	s_mov_b32 m0, s19
	s_nop 0
	global_load_lds_dwordx4 v128, s[58:59]
	s_mov_b32 m0, s21
	s_nop 0
	global_load_lds_dwordx4 v130, s[58:59]
	s_waitcnt vmcnt(8)
	s_waitcnt lgkmcnt(0)
	s_barrier
	s_setprio 1
	v_mfma_f32_16x16x32_bf16 v[92:95], v[142:145], v[178:181], v[92:95]
	v_mfma_f32_16x16x32_bf16 v[88:91], v[150:153], v[178:181], v[88:91]
	v_mfma_f32_16x16x32_bf16 v[36:39], v[142:145], v[186:189], v[36:39]
	v_mfma_f32_16x16x32_bf16 v[12:15], v[150:153], v[186:189], v[12:15]
	v_mfma_f32_16x16x32_bf16 v[32:35], v[142:145], v[200:203], v[32:35]
	v_mfma_f32_16x16x32_bf16 v[4:7], v[150:153], v[200:203], v[4:7]
	v_mfma_f32_16x16x32_bf16 v[76:79], v[142:145], v[218:221], v[76:79]
	v_mfma_f32_16x16x32_bf16 v[56:59], v[150:153], v[218:221], v[56:59]
	v_mfma_f32_16x16x32_bf16 v[92:95], v[146:149], v[182:185], v[92:95]
	v_mfma_f32_16x16x32_bf16 v[88:91], v[154:157], v[182:185], v[88:91]
	v_mfma_f32_16x16x32_bf16 v[36:39], v[146:149], v[196:199], v[36:39]
	v_mfma_f32_16x16x32_bf16 v[12:15], v[154:157], v[196:199], v[12:15]
	v_mfma_f32_16x16x32_bf16 v[32:35], v[146:149], v[204:207], v[32:35]
	v_mfma_f32_16x16x32_bf16 v[4:7], v[154:157], v[204:207], v[4:7]
	v_mfma_f32_16x16x32_bf16 v[76:79], v[146:149], v[222:225], v[76:79]
	v_mfma_f32_16x16x32_bf16 v[56:59], v[154:157], v[222:225], v[56:59]
	s_setprio 0
	s_setprio 1
	v_mfma_f32_16x16x32_bf16 v[84:87], v[158:161], v[178:181], v[84:87]
	v_mfma_f32_16x16x32_bf16 v[80:83], v[166:169], v[178:181], v[80:83]
	v_mfma_f32_16x16x32_bf16 v[28:31], v[158:161], v[186:189], v[28:31]
	v_mfma_f32_16x16x32_bf16 v[8:11], v[166:169], v[186:189], v[8:11]
	v_mfma_f32_16x16x32_bf16 v[24:27], v[158:161], v[200:203], v[24:27]
	v_mfma_f32_16x16x32_bf16 v[0:3], v[166:169], v[200:203], v[0:3]
	v_mfma_f32_16x16x32_bf16 v[72:75], v[158:161], v[218:221], v[72:75]
	v_mfma_f32_16x16x32_bf16 v[40:43], v[166:169], v[218:221], v[40:43]
	v_mfma_f32_16x16x32_bf16 v[84:87], v[162:165], v[182:185], v[84:87]
	v_mfma_f32_16x16x32_bf16 v[80:83], v[170:173], v[182:185], v[80:83]
	v_mfma_f32_16x16x32_bf16 v[28:31], v[162:165], v[196:199], v[28:31]
	v_mfma_f32_16x16x32_bf16 v[8:11], v[170:173], v[196:199], v[8:11]
	v_mfma_f32_16x16x32_bf16 v[24:27], v[162:165], v[204:207], v[24:27]
	v_mfma_f32_16x16x32_bf16 v[0:3], v[170:173], v[204:207], v[0:3]
	v_mfma_f32_16x16x32_bf16 v[72:75], v[162:165], v[222:225], v[72:75]
	s_setprio 2
	s_barrier
; #define PG8_STAGE(bufoff, gbase, voff) do { _Pragma("unroll") for (int _i = 0; _i < 2; ++_i) \
;         __builtin_amdgcn_global_load_lds((const unsigned*)((const char*)(gbase) + (voff)[_i]), (LAS unsigned*)(lds + (bufoff) + ldsw + _i * 8192), 16, 0, 0); } while (0)
; #define PG8_LDA(dst, b, h) do { _Pragma("unroll") for (int m = 0; m < 4; ++m) _Pragma("unroll") for (int k = 0; k < 2; ++k) dst[m][k] = *(const LAS bf16x8*)(lds + PG8_SA(b, h) + aoff + m * 2048 + k * 1024); } while (0)
; #define PG8_LDB(dst, b, h) do { _Pragma("unroll") for (int n = 0; n < 2; ++n) _Pragma("unroll") for (int k = 0; k < 2; ++k) dst[n][k] = *(const LAS bf16x8*)(lds + PG8_SB(b, h) + boff + n * 2048 + k * 1024); } while (0)
; #define PG8_MMA(ai, bj, At, Bt) do { __builtin_amdgcn_s_setprio(1); _Pragma("unroll") for (int m = 0; m < 4; ++m) _Pragma("unroll") for (int n = 0; n < 2; ++n) _Pragma("unroll") for (int k = 0; k < 2; ++k) \
;         acc[ai][bj][m][n] = __builtin_amdgcn_mfma_f32_16x16x32_bf16(Bt[n][k], At[m][k], acc[ai][bj][m][n], 0, 0, 0); __builtin_amdgcn_s_setprio(0); } while (0)
; #define PG8_WAIT_V(n) asm volatile("s_waitcnt vmcnt(" #n ")" ::: "memory")
; #define PG8_WAIT_L(n) asm volatile("s_waitcnt lgkmcnt(" #n ")" ::: "memory")
; #define PG8_BAR __builtin_amdgcn_s_barrier()
; #define PG8_SCHED __builtin_amdgcn_sched_barrier(0)
; template <class Epi, bool KREV = false>
; __device__ __forceinline__ void gemm_phase(LAS unsigned char* lds, const Gemm g, const StaticOrder& S, const Epi& E, int wave_s) {
;     ...
;             PG8_LDB(B0, 1, 0); PG8_LDB(B1, 1, 1); PG8_SCHED; PG8_LDA(At, 1, 0); PG8_STAGE(PG8_SA(0, 1), a2 + hstep, voffA);
;             PG8_WAIT_V(8); PG8_WAIT_L(0); PG8_BAR; PG8_MMA(0, 0, At, B0); PG8_MMA(0, 1, At, B1); PG8_BAR; PG8_SCHED;
;             PG8_LDA(At, 1, 1); PG8_STAGE(PG8_SB(1, 0), b3, voffB); PG8_STAGE(PG8_SB(1, 1), b3 + bh, voffB); PG8_STAGE(PG8_SA(1, 0), a3, voffA);
;             PG8_WAIT_V(8); PG8_WAIT_L(0); PG8_BAR; PG8_MMA(1, 0, At, B0); PG8_MMA(1, 1, At, B1); PG8_BAR; PG8_SCHED;
	v_mfma_f32_16x16x32_bf16 v[40:43], v[170:173], v[222:225], v[40:43]
	s_setprio 0
	s_add_i32 s84, 0, 0x18000
	s_add_i32 s85, 0, 0x1c000
	v_add_u32_e32 v154, s84, v135
	v_add_u32_e32 v170, s85, v135
	ds_read_b128 v[142:145], v154
	ds_read_b128 v[146:149], v154 offset:1024
	ds_read_b128 v[150:153], v154 offset:2048
	ds_read_b128 v[154:157], v154 offset:3072
	ds_read_b128 v[158:161], v170
	ds_read_b128 v[162:165], v170 offset:1024
	ds_read_b128 v[166:169], v170 offset:2048
	ds_read_b128 v[170:173], v170 offset:3072
	s_add_u32 s58, s58, 0x80000
	s_addc_u32 s59, s59, 0
	s_mov_b32 m0, s67
	ds_read_b128 v[178:181], v194 offset:32768
	ds_read_b128 v[182:185], v194 offset:33792
	ds_read_b128 v[186:189], v194 offset:34816
	ds_read_b128 v[196:199], v194 offset:35840
	ds_read_b128 v[200:203], v194 offset:36864
	ds_read_b128 v[204:207], v194 offset:37888
	ds_read_b128 v[218:221], v194 offset:38912
	ds_read_b128 v[222:225], v194 offset:39936
	global_load_lds_dwordx4 v128, s[58:59]
	s_mov_b32 m0, s68
	s_nop 0
	global_load_lds_dwordx4 v130, s[58:59]
	s_waitcnt vmcnt(8)
	s_waitcnt lgkmcnt(0)
	s_barrier
	s_setprio 1
	v_mfma_f32_16x16x32_bf16 v[124:127], v[142:145], v[178:181], v[124:127]
	v_mfma_f32_16x16x32_bf16 v[120:123], v[150:153], v[178:181], v[120:123]
	v_mfma_f32_16x16x32_bf16 v[68:71], v[142:145], v[186:189], v[68:71]
	v_mfma_f32_16x16x32_bf16 v[64:67], v[150:153], v[186:189], v[64:67]
	v_mfma_f32_16x16x32_bf16 v[60:63], v[142:145], v[200:203], v[60:63]
	v_mfma_f32_16x16x32_bf16 v[20:23], v[150:153], v[200:203], v[20:23]
	v_mfma_f32_16x16x32_bf16 v[108:111], v[142:145], v[218:221], v[108:111]
	v_mfma_f32_16x16x32_bf16 v[104:107], v[150:153], v[218:221], v[104:107]
	v_mfma_f32_16x16x32_bf16 v[124:127], v[146:149], v[182:185], v[124:127]
	v_mfma_f32_16x16x32_bf16 v[120:123], v[154:157], v[182:185], v[120:123]
	v_mfma_f32_16x16x32_bf16 v[68:71], v[146:149], v[196:199], v[68:71]
	v_mfma_f32_16x16x32_bf16 v[64:67], v[154:157], v[196:199], v[64:67]
	v_mfma_f32_16x16x32_bf16 v[60:63], v[146:149], v[204:207], v[60:63]
	v_mfma_f32_16x16x32_bf16 v[20:23], v[154:157], v[204:207], v[20:23]
	v_mfma_f32_16x16x32_bf16 v[108:111], v[146:149], v[222:225], v[108:111]
	v_mfma_f32_16x16x32_bf16 v[104:107], v[154:157], v[222:225], v[104:107]
	s_setprio 0
	s_setprio 1
	v_mfma_f32_16x16x32_bf16 v[116:119], v[158:161], v[178:181], v[116:119]
	v_mfma_f32_16x16x32_bf16 v[112:115], v[166:169], v[178:181], v[112:115]
	v_mfma_f32_16x16x32_bf16 v[52:55], v[158:161], v[186:189], v[52:55]
	v_mfma_f32_16x16x32_bf16 v[48:51], v[166:169], v[186:189], v[48:51]
	v_mfma_f32_16x16x32_bf16 v[44:47], v[158:161], v[200:203], v[44:47]
	v_mfma_f32_16x16x32_bf16 v[16:19], v[166:169], v[200:203], v[16:19]
	v_mfma_f32_16x16x32_bf16 v[100:103], v[158:161], v[218:221], v[100:103]
	v_mfma_f32_16x16x32_bf16 v[96:99], v[166:169], v[218:221], v[96:99]
	v_mfma_f32_16x16x32_bf16 v[116:119], v[162:165], v[182:185], v[116:119]
	v_mfma_f32_16x16x32_bf16 v[112:115], v[170:173], v[182:185], v[112:115]
	v_mfma_f32_16x16x32_bf16 v[52:55], v[162:165], v[196:199], v[52:55]
	v_mfma_f32_16x16x32_bf16 v[48:51], v[170:173], v[196:199], v[48:51]
	v_mfma_f32_16x16x32_bf16 v[44:47], v[162:165], v[204:207], v[44:47]
	v_mfma_f32_16x16x32_bf16 v[16:19], v[170:173], v[204:207], v[16:19]
	v_mfma_f32_16x16x32_bf16 v[100:103], v[162:165], v[222:225], v[100:103]
	s_setprio 2
	s_barrier
	v_mfma_f32_16x16x32_bf16 v[96:99], v[170:173], v[222:225], v[96:99]
	s_setprio 0
	s_add_i32 s58, s84, s66
	s_mov_b32 m0, s58
	ds_read_b128 v[178:181], v194 offset:49152
	ds_read_b128 v[182:185], v194 offset:50176
	ds_read_b128 v[186:189], v194 offset:51200
	ds_read_b128 v[196:199], v194 offset:52224
	ds_read_b128 v[200:203], v194 offset:53248
	ds_read_b128 v[204:207], v194 offset:54272
	ds_read_b128 v[218:221], v194 offset:55296
	ds_read_b128 v[222:225], v194 offset:56320
	global_load_lds_dwordx4 v176, s[98:99]
	s_add_i32 m0, s58, 0x2000
	s_add_u32 s56, s56, 0x1600080
	s_addc_u32 s57, s57, 0
	s_add_i32 s58, s85, s66
	global_load_lds_dwordx4 v132, s[98:99]
	s_mov_b32 m0, s58
	s_nop 0
	global_load_lds_dwordx4 v176, s[56:57]
	s_add_i32 m0, s58, 0x2000
	s_nop 0
	global_load_lds_dwordx4 v132, s[56:57]
	s_mov_b32 m0, s70
	s_nop 0
	global_load_lds_dwordx4 v128, s[100:101]
	s_mov_b32 m0, s71
	s_nop 0
	global_load_lds_dwordx4 v130, s[100:101]
	s_waitcnt vmcnt(8)
	s_waitcnt lgkmcnt(0)
	s_barrier
	s_setprio 1
	v_mfma_f32_16x16x32_bf16 v[92:95], v[142:145], v[178:181], v[92:95]
	v_mfma_f32_16x16x32_bf16 v[88:91], v[150:153], v[178:181], v[88:91]
	v_mfma_f32_16x16x32_bf16 v[36:39], v[142:145], v[186:189], v[36:39]
	v_mfma_f32_16x16x32_bf16 v[12:15], v[150:153], v[186:189], v[12:15]
	v_mfma_f32_16x16x32_bf16 v[32:35], v[142:145], v[200:203], v[32:35]
	v_mfma_f32_16x16x32_bf16 v[4:7], v[150:153], v[200:203], v[4:7]
	v_mfma_f32_16x16x32_bf16 v[76:79], v[142:145], v[218:221], v[76:79]
	v_mfma_f32_16x16x32_bf16 v[56:59], v[150:153], v[218:221], v[56:59]
	v_mfma_f32_16x16x32_bf16 v[92:95], v[146:149], v[182:185], v[92:95]
	v_mfma_f32_16x16x32_bf16 v[88:91], v[154:157], v[182:185], v[88:91]
	v_mfma_f32_16x16x32_bf16 v[36:39], v[146:149], v[196:199], v[36:39]
	v_mfma_f32_16x16x32_bf16 v[12:15], v[154:157], v[196:199], v[12:15]
	v_mfma_f32_16x16x32_bf16 v[32:35], v[146:149], v[204:207], v[32:35]
	v_mfma_f32_16x16x32_bf16 v[4:7], v[154:157], v[204:207], v[4:7]
	v_mfma_f32_16x16x32_bf16 v[76:79], v[146:149], v[222:225], v[76:79]
	v_mfma_f32_16x16x32_bf16 v[56:59], v[154:157], v[222:225], v[56:59]
	s_setprio 0
	s_setprio 1
	v_mfma_f32_16x16x32_bf16 v[84:87], v[158:161], v[178:181], v[84:87]
	v_mfma_f32_16x16x32_bf16 v[80:83], v[166:169], v[178:181], v[80:83]
	v_mfma_f32_16x16x32_bf16 v[28:31], v[158:161], v[186:189], v[28:31]
	v_mfma_f32_16x16x32_bf16 v[8:11], v[166:169], v[186:189], v[8:11]
	v_mfma_f32_16x16x32_bf16 v[24:27], v[158:161], v[200:203], v[24:27]
	v_mfma_f32_16x16x32_bf16 v[0:3], v[166:169], v[200:203], v[0:3]
	v_mfma_f32_16x16x32_bf16 v[72:75], v[158:161], v[218:221], v[72:75]
	v_mfma_f32_16x16x32_bf16 v[40:43], v[166:169], v[218:221], v[40:43]
	v_mfma_f32_16x16x32_bf16 v[84:87], v[162:165], v[182:185], v[84:87]
	v_mfma_f32_16x16x32_bf16 v[80:83], v[170:173], v[182:185], v[80:83]
	v_mfma_f32_16x16x32_bf16 v[28:31], v[162:165], v[196:199], v[28:31]
	v_mfma_f32_16x16x32_bf16 v[8:11], v[170:173], v[196:199], v[8:11]
	s_add_i32 s83, s83, 2
	s_add_u32 s54, s54, 0x100
	s_addc_u32 s55, s55, 0
	v_mfma_f32_16x16x32_bf16 v[24:27], v[162:165], v[204:207], v[24:27]
	s_add_u32 s80, s80, 0x100
	s_addc_u32 s82, s82, 0
	v_mfma_f32_16x16x32_bf16 v[0:3], v[170:173], v[204:207], v[0:3]
	s_cmp_gt_u32 s83, 29
	v_mfma_f32_16x16x32_bf16 v[72:75], v[162:165], v[222:225], v[72:75]
	s_setprio 2
	s_barrier
	v_mfma_f32_16x16x32_bf16 v[40:43], v[170:173], v[222:225], v[40:43]
	s_setprio 0
	s_cbranch_scc0 .LBB0_836
	s_and_b64 vcc, exec, s[38:39]
	s_cbranch_vccz .LBB0_839
	s_barrier

; #define PG8_STAGE(bufoff, gbase, voff) do { _Pragma("unroll") for (int _i = 0; _i < 2; ++_i) \
;         __builtin_amdgcn_global_load_lds((const unsigned*)((const char*)(gbase) + (voff)[_i]), (LAS unsigned*)(lds + (bufoff) + ldsw + _i * 8192), 16, 0, 0); } while (0)
; #define PG8_LDA(dst, b, h) do { _Pragma("unroll") for (int m = 0; m < 4; ++m) _Pragma("unroll") for (int k = 0; k < 2; ++k) dst[m][k] = *(const LAS bf16x8*)(lds + PG8_SA(b, h) + aoff + m * 2048 + k * 1024); } while (0)
; #define PG8_LDB(dst, b, h) do { _Pragma("unroll") for (int n = 0; n < 2; ++n) _Pragma("unroll") for (int k = 0; k < 2; ++k) dst[n][k] = *(const LAS bf16x8*)(lds + PG8_SB(b, h) + boff + n * 2048 + k * 1024); } while (0)
; #define PG8_MMA(ai, bj, At, Bt) do { __builtin_amdgcn_s_setprio(1); _Pragma("unroll") for (int m = 0; m < 4; ++m) _Pragma("unroll") for (int n = 0; n < 2; ++n) _Pragma("unroll") for (int k = 0; k < 2; ++k) \
;         acc[ai][bj][m][n] = __builtin_amdgcn_mfma_f32_16x16x32_bf16(Bt[n][k], At[m][k], acc[ai][bj][m][n], 0, 0, 0); __builtin_amdgcn_s_setprio(0); } while (0)
; #define PG8_WAIT_V(n) asm volatile("s_waitcnt vmcnt(" #n ")" ::: "memory")
; #define PG8_WAIT_L(n) asm volatile("s_waitcnt lgkmcnt(" #n ")" ::: "memory")
; #define PG8_BAR __builtin_amdgcn_s_barrier()
; #define PG8_SCHED __builtin_amdgcn_sched_barrier(0)
; template <class Epi, bool KREV = false>
; __device__ __forceinline__ void gemm_phase(LAS unsigned char* lds, const Gemm g, const StaticOrder& S, const Epi& E, int wave_s) {
;     ...
;             PG8_LDB(B0, 0, 0); PG8_LDB(B1, 0, 1); PG8_SCHED; PG8_LDA(At, 0, 0); PG8_STAGE(PG8_SA(1, 1), a1 + hstep, voffA);
;             PG8_WAIT_V(8); PG8_WAIT_L(0); PG8_BAR; PG8_MMA(0, 0, At, B0); PG8_MMA(0, 1, At, B1); PG8_BAR; PG8_SCHED;
;             PG8_LDA(At, 0, 1); PG8_STAGE(PG8_SB(0, 0), b2, voffB); PG8_STAGE(PG8_SB(0, 1), b2 + bh, voffB); PG8_STAGE(PG8_SA(0, 0), a2, voffA);
;             PG8_WAIT_V(8); PG8_WAIT_L(0); PG8_BAR; PG8_MMA(1, 0, At, B0); PG8_MMA(1, 1, At, B1); PG8_BAR; PG8_SCHED;
.LBB0_1023:
	s_or_b32 s80, s44, 1
	s_lshl_b64 s[46:47], s[80:81], 7
	s_sub_u32 s23, 0, s46
	s_subb_u32 s45, 0, s47
	s_add_i32 s48, 0, 0x10000
	s_add_i32 s49, 0, 0x14000
	s_add_u32 s46, s42, s23
	s_addc_u32 s47, s43, s45
	s_add_i32 m0, s28, 0xc000
	s_nop 0
	global_load_lds_dwordx4 v156, s[46:47]
	s_add_i32 m0, s28, 0xe000
	s_nop 0
	global_load_lds_dwordx4 v154, s[46:47]
	s_waitcnt vmcnt(8)
	s_waitcnt lgkmcnt(0)
	s_barrier
	s_setprio 1
	v_mfma_f32_16x16x32_bf16 v[132:135], v[112:115], v[218:221], v[132:135]
	v_mfma_f32_16x16x32_bf16 v[120:123], v[136:139], v[218:221], v[120:123]
	v_mfma_f32_16x16x32_bf16 v[108:111], v[112:115], v[226:229], v[108:111]
	v_mfma_f32_16x16x32_bf16 v[104:107], v[136:139], v[226:229], v[104:107]
	v_mfma_f32_16x16x32_bf16 v[92:95], v[112:115], v[234:237], v[92:95]
	v_mfma_f32_16x16x32_bf16 v[88:91], v[136:139], v[234:237], v[88:91]
	v_mfma_f32_16x16x32_bf16 v[76:79], v[112:115], v[242:245], v[76:79]
	v_mfma_f32_16x16x32_bf16 v[72:75], v[136:139], v[242:245], v[72:75]
	v_mfma_f32_16x16x32_bf16 v[132:135], v[124:127], v[222:225], v[132:135]
	v_mfma_f32_16x16x32_bf16 v[120:123], v[140:143], v[222:225], v[120:123]
	v_mfma_f32_16x16x32_bf16 v[108:111], v[124:127], v[230:233], v[108:111]
	v_mfma_f32_16x16x32_bf16 v[104:107], v[140:143], v[230:233], v[104:107]
	v_mfma_f32_16x16x32_bf16 v[92:95], v[124:127], v[238:241], v[92:95]
	v_mfma_f32_16x16x32_bf16 v[88:91], v[140:143], v[238:241], v[88:91]
	v_mfma_f32_16x16x32_bf16 v[76:79], v[124:127], v[246:249], v[76:79]
	v_mfma_f32_16x16x32_bf16 v[72:75], v[140:143], v[246:249], v[72:75]
	s_setprio 0
	s_setprio 1
	v_mfma_f32_16x16x32_bf16 v[128:131], v[144:147], v[218:221], v[128:131]
	v_mfma_f32_16x16x32_bf16 v[116:119], v[194:197], v[218:221], v[116:119]
	v_mfma_f32_16x16x32_bf16 v[100:103], v[144:147], v[226:229], v[100:103]
	v_mfma_f32_16x16x32_bf16 v[96:99], v[194:197], v[226:229], v[96:99]
	v_mfma_f32_16x16x32_bf16 v[84:87], v[144:147], v[234:237], v[84:87]
	v_mfma_f32_16x16x32_bf16 v[80:83], v[194:197], v[234:237], v[80:83]
	v_mfma_f32_16x16x32_bf16 v[68:71], v[144:147], v[242:245], v[68:71]
	v_mfma_f32_16x16x32_bf16 v[64:67], v[194:197], v[242:245], v[64:67]
	v_mfma_f32_16x16x32_bf16 v[128:131], v[148:151], v[222:225], v[128:131]
	v_mfma_f32_16x16x32_bf16 v[116:119], v[202:205], v[222:225], v[116:119]
	v_mfma_f32_16x16x32_bf16 v[100:103], v[148:151], v[230:233], v[100:103]
	v_mfma_f32_16x16x32_bf16 v[96:99], v[202:205], v[230:233], v[96:99]
	v_mfma_f32_16x16x32_bf16 v[84:87], v[148:151], v[238:241], v[84:87]
	v_mfma_f32_16x16x32_bf16 v[80:83], v[202:205], v[238:241], v[80:83]
	v_mfma_f32_16x16x32_bf16 v[68:71], v[148:151], v[246:249], v[68:71]
	s_setprio 2
	s_barrier
	v_mfma_f32_16x16x32_bf16 v[64:67], v[202:205], v[246:249], v[64:67]
	s_setprio 0
	s_add_u32 s98, s24, s78
	s_addc_u32 s99, s25, s79
	s_add_u32 s100, s26, s78
	s_addc_u32 s101, s27, s79
	s_add_i32 s23, s48, s1
	s_mov_b32 m0, s23
	ds_read_b128 v[218:221], v201 offset:16384
	ds_read_b128 v[222:225], v201 offset:17408
	ds_read_b128 v[226:229], v201 offset:18432
	ds_read_b128 v[230:233], v201 offset:19456
	ds_read_b128 v[234:237], v201 offset:20480
	ds_read_b128 v[238:241], v201 offset:21504
	ds_read_b128 v[242:245], v201 offset:22528
	ds_read_b128 v[246:249], v201 offset:23552
	global_load_lds_dwordx4 v176, s[24:25]
	s_add_i32 m0, s23, 0x2000
	s_add_u32 s46, s24, 0x160000
	s_addc_u32 s47, s25, 0
	s_add_i32 s23, s49, s1
	global_load_lds_dwordx4 v152, s[24:25]
	s_mov_b32 m0, s23
	s_nop 0
	global_load_lds_dwordx4 v176, s[46:47]
	s_add_i32 m0, s23, 0x2000
	s_nop 0
	global_load_lds_dwordx4 v152, s[46:47]
	s_mov_b32 m0, s28
	s_nop 0
	global_load_lds_dwordx4 v156, s[26:27]
	s_mov_b32 m0, s29
	s_nop 0
	global_load_lds_dwordx4 v154, s[26:27]
	s_waitcnt vmcnt(8)
	s_waitcnt lgkmcnt(0)
	s_barrier
	s_setprio 1
	v_mfma_f32_16x16x32_bf16 v[60:63], v[112:115], v[218:221], v[60:63]
	v_mfma_f32_16x16x32_bf16 v[56:59], v[136:139], v[218:221], v[56:59]
	v_mfma_f32_16x16x32_bf16 v[44:47], v[112:115], v[226:229], v[44:47]
	v_mfma_f32_16x16x32_bf16 v[40:43], v[136:139], v[226:229], v[40:43]
	v_mfma_f32_16x16x32_bf16 v[28:31], v[112:115], v[234:237], v[28:31]
	v_mfma_f32_16x16x32_bf16 v[24:27], v[136:139], v[234:237], v[24:27]
	v_mfma_f32_16x16x32_bf16 v[12:15], v[112:115], v[242:245], v[12:15]
	v_mfma_f32_16x16x32_bf16 v[8:11], v[136:139], v[242:245], v[8:11]
	v_mfma_f32_16x16x32_bf16 v[60:63], v[124:127], v[222:225], v[60:63]
	v_mfma_f32_16x16x32_bf16 v[56:59], v[140:143], v[222:225], v[56:59]
	v_mfma_f32_16x16x32_bf16 v[44:47], v[124:127], v[230:233], v[44:47]
	v_mfma_f32_16x16x32_bf16 v[40:43], v[140:143], v[230:233], v[40:43]
	v_mfma_f32_16x16x32_bf16 v[28:31], v[124:127], v[238:241], v[28:31]
	v_mfma_f32_16x16x32_bf16 v[24:27], v[140:143], v[238:241], v[24:27]
	v_mfma_f32_16x16x32_bf16 v[12:15], v[124:127], v[246:249], v[12:15]
	v_mfma_f32_16x16x32_bf16 v[8:11], v[140:143], v[246:249], v[8:11]
	s_setprio 0
	s_setprio 1
	v_mfma_f32_16x16x32_bf16 v[52:55], v[144:147], v[218:221], v[52:55]
	v_mfma_f32_16x16x32_bf16 v[48:51], v[194:197], v[218:221], v[48:51]
	v_mfma_f32_16x16x32_bf16 v[36:39], v[144:147], v[226:229], v[36:39]
	v_mfma_f32_16x16x32_bf16 v[32:35], v[194:197], v[226:229], v[32:35]
	v_mfma_f32_16x16x32_bf16 v[20:23], v[144:147], v[234:237], v[20:23]
	v_mfma_f32_16x16x32_bf16 v[16:19], v[194:197], v[234:237], v[16:19]
	v_mfma_f32_16x16x32_bf16 v[4:7], v[144:147], v[242:245], v[4:7]
	v_mfma_f32_16x16x32_bf16 v[0:3], v[194:197], v[242:245], v[0:3]
	v_mfma_f32_16x16x32_bf16 v[52:55], v[148:151], v[222:225], v[52:55]
	v_mfma_f32_16x16x32_bf16 v[48:51], v[202:205], v[222:225], v[48:51]
	v_mfma_f32_16x16x32_bf16 v[36:39], v[148:151], v[230:233], v[36:39]
	v_mfma_f32_16x16x32_bf16 v[32:35], v[202:205], v[230:233], v[32:35]
	v_mfma_f32_16x16x32_bf16 v[20:23], v[148:151], v[238:241], v[20:23]
	v_mfma_f32_16x16x32_bf16 v[16:19], v[202:205], v[238:241], v[16:19]
	v_mfma_f32_16x16x32_bf16 v[4:7], v[148:151], v[246:249], v[4:7]
	s_setprio 2
	s_barrier
; #define PG8_STAGE(bufoff, gbase, voff) do { _Pragma("unroll") for (int _i = 0; _i < 2; ++_i) \
;         __builtin_amdgcn_global_load_lds((const unsigned*)((const char*)(gbase) + (voff)[_i]), (LAS unsigned*)(lds + (bufoff) + ldsw + _i * 8192), 16, 0, 0); } while (0)
; #define PG8_LDA(dst, b, h) do { _Pragma("unroll") for (int m = 0; m < 4; ++m) _Pragma("unroll") for (int k = 0; k < 2; ++k) dst[m][k] = *(const LAS bf16x8*)(lds + PG8_SA(b, h) + aoff + m * 2048 + k * 1024); } while (0)
; #define PG8_LDB(dst, b, h) do { _Pragma("unroll") for (int n = 0; n < 2; ++n) _Pragma("unroll") for (int k = 0; k < 2; ++k) dst[n][k] = *(const LAS bf16x8*)(lds + PG8_SB(b, h) + boff + n * 2048 + k * 1024); } while (0)
; #define PG8_MMA(ai, bj, At, Bt) do { __builtin_amdgcn_s_setprio(1); _Pragma("unroll") for (int m = 0; m < 4; ++m) _Pragma("unroll") for (int n = 0; n < 2; ++n) _Pragma("unroll") for (int k = 0; k < 2; ++k) \
;         acc[ai][bj][m][n] = __builtin_amdgcn_mfma_f32_16x16x32_bf16(Bt[n][k], At[m][k], acc[ai][bj][m][n], 0, 0, 0); __builtin_amdgcn_s_setprio(0); } while (0)
; #define PG8_WAIT_V(n) asm volatile("s_waitcnt vmcnt(" #n ")" ::: "memory")
; #define PG8_WAIT_L(n) asm volatile("s_waitcnt lgkmcnt(" #n ")" ::: "memory")
; #define PG8_BAR __builtin_amdgcn_s_barrier()
; #define PG8_SCHED __builtin_amdgcn_sched_barrier(0)
; template <class Epi, bool KREV = false>
; __device__ __forceinline__ void gemm_phase(LAS unsigned char* lds, const Gemm g, const StaticOrder& S, const Epi& E, int wave_s) {
;     ...
;             PG8_LDB(B0, 1, 0); PG8_LDB(B1, 1, 1); PG8_SCHED; PG8_LDA(At, 1, 0); PG8_STAGE(PG8_SA(0, 1), a2 + hstep, voffA);
;             PG8_WAIT_V(8); PG8_WAIT_L(0); PG8_BAR; PG8_MMA(0, 0, At, B0); PG8_MMA(0, 1, At, B1); PG8_BAR; PG8_SCHED;
;             PG8_LDA(At, 1, 1); PG8_STAGE(PG8_SB(1, 0), b3, voffB); PG8_STAGE(PG8_SB(1, 1), b3 + bh, voffB); PG8_STAGE(PG8_SA(1, 0), a3, voffA);
;             PG8_WAIT_V(8); PG8_WAIT_L(0); PG8_BAR; PG8_MMA(1, 0, At, B0); PG8_MMA(1, 1, At, B1); PG8_BAR; PG8_SCHED;
	v_mfma_f32_16x16x32_bf16 v[0:3], v[202:205], v[246:249], v[0:3]
	s_setprio 0
	s_add_i32 s23, 0, 0x18000
	s_add_i32 s45, 0, 0x1c000
	v_add_u32_e32 v140, s23, v199
	v_add_u32_e32 v202, s45, v199
	ds_read_b128 v[112:115], v140
	ds_read_b128 v[124:127], v140 offset:1024
	ds_read_b128 v[136:139], v140 offset:2048
	ds_read_b128 v[140:143], v140 offset:3072
	ds_read_b128 v[144:147], v202
	ds_read_b128 v[148:151], v202 offset:1024
	ds_read_b128 v[194:197], v202 offset:2048
	ds_read_b128 v[202:205], v202 offset:3072
	s_add_u32 s26, s26, 0x160000
	s_addc_u32 s27, s27, 0
	s_mov_b32 m0, s30
	ds_read_b128 v[218:221], v201 offset:32768
	ds_read_b128 v[222:225], v201 offset:33792
	ds_read_b128 v[226:229], v201 offset:34816
	ds_read_b128 v[230:233], v201 offset:35840
	ds_read_b128 v[234:237], v201 offset:36864
	ds_read_b128 v[238:241], v201 offset:37888
	ds_read_b128 v[242:245], v201 offset:38912
	ds_read_b128 v[246:249], v201 offset:39936
	global_load_lds_dwordx4 v156, s[26:27]
	s_mov_b32 m0, s34
	s_nop 0
	global_load_lds_dwordx4 v154, s[26:27]
	s_waitcnt vmcnt(8)
	s_waitcnt lgkmcnt(0)
	s_barrier
	s_setprio 1
	v_mfma_f32_16x16x32_bf16 v[132:135], v[112:115], v[218:221], v[132:135]
	v_mfma_f32_16x16x32_bf16 v[120:123], v[136:139], v[218:221], v[120:123]
	v_mfma_f32_16x16x32_bf16 v[108:111], v[112:115], v[226:229], v[108:111]
	v_mfma_f32_16x16x32_bf16 v[104:107], v[136:139], v[226:229], v[104:107]
	v_mfma_f32_16x16x32_bf16 v[92:95], v[112:115], v[234:237], v[92:95]
	v_mfma_f32_16x16x32_bf16 v[88:91], v[136:139], v[234:237], v[88:91]
	v_mfma_f32_16x16x32_bf16 v[76:79], v[112:115], v[242:245], v[76:79]
	v_mfma_f32_16x16x32_bf16 v[72:75], v[136:139], v[242:245], v[72:75]
	v_mfma_f32_16x16x32_bf16 v[132:135], v[124:127], v[222:225], v[132:135]
	v_mfma_f32_16x16x32_bf16 v[120:123], v[140:143], v[222:225], v[120:123]
	v_mfma_f32_16x16x32_bf16 v[108:111], v[124:127], v[230:233], v[108:111]
	v_mfma_f32_16x16x32_bf16 v[104:107], v[140:143], v[230:233], v[104:107]
	v_mfma_f32_16x16x32_bf16 v[92:95], v[124:127], v[238:241], v[92:95]
	v_mfma_f32_16x16x32_bf16 v[88:91], v[140:143], v[238:241], v[88:91]
	v_mfma_f32_16x16x32_bf16 v[76:79], v[124:127], v[246:249], v[76:79]
	v_mfma_f32_16x16x32_bf16 v[72:75], v[140:143], v[246:249], v[72:75]
	s_setprio 0
	s_setprio 1
	v_mfma_f32_16x16x32_bf16 v[128:131], v[144:147], v[218:221], v[128:131]
	v_mfma_f32_16x16x32_bf16 v[116:119], v[194:197], v[218:221], v[116:119]
	v_mfma_f32_16x16x32_bf16 v[100:103], v[144:147], v[226:229], v[100:103]
	v_mfma_f32_16x16x32_bf16 v[96:99], v[194:197], v[226:229], v[96:99]
	v_mfma_f32_16x16x32_bf16 v[84:87], v[144:147], v[234:237], v[84:87]
	v_mfma_f32_16x16x32_bf16 v[80:83], v[194:197], v[234:237], v[80:83]
	v_mfma_f32_16x16x32_bf16 v[68:71], v[144:147], v[242:245], v[68:71]
	v_mfma_f32_16x16x32_bf16 v[64:67], v[194:197], v[242:245], v[64:67]
	v_mfma_f32_16x16x32_bf16 v[128:131], v[148:151], v[222:225], v[128:131]
	v_mfma_f32_16x16x32_bf16 v[116:119], v[202:205], v[222:225], v[116:119]
	v_mfma_f32_16x16x32_bf16 v[100:103], v[148:151], v[230:233], v[100:103]
	v_mfma_f32_16x16x32_bf16 v[96:99], v[202:205], v[230:233], v[96:99]
	v_mfma_f32_16x16x32_bf16 v[84:87], v[148:151], v[238:241], v[84:87]
	v_mfma_f32_16x16x32_bf16 v[80:83], v[202:205], v[238:241], v[80:83]
	v_mfma_f32_16x16x32_bf16 v[68:71], v[148:151], v[246:249], v[68:71]
	s_setprio 2
	s_barrier
	v_mfma_f32_16x16x32_bf16 v[64:67], v[202:205], v[246:249], v[64:67]
	s_setprio 0
	s_add_i32 s23, s23, s1
	s_mov_b32 m0, s23
	ds_read_b128 v[218:221], v201 offset:49152
	ds_read_b128 v[222:225], v201 offset:50176
	ds_read_b128 v[226:229], v201 offset:51200
	ds_read_b128 v[230:233], v201 offset:52224
	ds_read_b128 v[234:237], v201 offset:53248
	ds_read_b128 v[238:241], v201 offset:54272
	ds_read_b128 v[242:245], v201 offset:55296
	ds_read_b128 v[246:249], v201 offset:56320
	global_load_lds_dwordx4 v176, s[98:99]
	s_add_i32 m0, s23, 0x2000
	s_add_u32 s24, s24, 0x15ff80
	s_addc_u32 s25, s25, 0
	s_add_i32 s23, s45, s1
	global_load_lds_dwordx4 v152, s[98:99]
	s_mov_b32 m0, s23
	s_nop 0
	global_load_lds_dwordx4 v176, s[24:25]
	s_add_i32 m0, s23, 0x2000
	s_nop 0
	global_load_lds_dwordx4 v152, s[24:25]
	s_mov_b32 m0, s36
	s_nop 0
	global_load_lds_dwordx4 v156, s[100:101]
	s_mov_b32 m0, s37
	s_nop 0
	global_load_lds_dwordx4 v154, s[100:101]
	s_waitcnt vmcnt(8)
	s_waitcnt lgkmcnt(0)
	s_barrier
	s_setprio 1
	v_mfma_f32_16x16x32_bf16 v[60:63], v[112:115], v[218:221], v[60:63]
	v_mfma_f32_16x16x32_bf16 v[56:59], v[136:139], v[218:221], v[56:59]
	v_mfma_f32_16x16x32_bf16 v[44:47], v[112:115], v[226:229], v[44:47]
	v_mfma_f32_16x16x32_bf16 v[40:43], v[136:139], v[226:229], v[40:43]
	v_mfma_f32_16x16x32_bf16 v[28:31], v[112:115], v[234:237], v[28:31]
	v_mfma_f32_16x16x32_bf16 v[24:27], v[136:139], v[234:237], v[24:27]
	v_mfma_f32_16x16x32_bf16 v[12:15], v[112:115], v[242:245], v[12:15]
	v_mfma_f32_16x16x32_bf16 v[8:11], v[136:139], v[242:245], v[8:11]
	v_mfma_f32_16x16x32_bf16 v[60:63], v[124:127], v[222:225], v[60:63]
	v_mfma_f32_16x16x32_bf16 v[56:59], v[140:143], v[222:225], v[56:59]
	v_mfma_f32_16x16x32_bf16 v[44:47], v[124:127], v[230:233], v[44:47]
	v_mfma_f32_16x16x32_bf16 v[40:43], v[140:143], v[230:233], v[40:43]
	v_mfma_f32_16x16x32_bf16 v[28:31], v[124:127], v[238:241], v[28:31]
	v_mfma_f32_16x16x32_bf16 v[24:27], v[140:143], v[238:241], v[24:27]
	v_mfma_f32_16x16x32_bf16 v[12:15], v[124:127], v[246:249], v[12:15]
	v_mfma_f32_16x16x32_bf16 v[8:11], v[140:143], v[246:249], v[8:11]
	s_setprio 0
	s_setprio 1
	v_mfma_f32_16x16x32_bf16 v[52:55], v[144:147], v[218:221], v[52:55]
	v_mfma_f32_16x16x32_bf16 v[48:51], v[194:197], v[218:221], v[48:51]
	v_mfma_f32_16x16x32_bf16 v[36:39], v[144:147], v[226:229], v[36:39]
	v_mfma_f32_16x16x32_bf16 v[32:35], v[194:197], v[226:229], v[32:35]
	v_mfma_f32_16x16x32_bf16 v[20:23], v[144:147], v[234:237], v[20:23]
	v_mfma_f32_16x16x32_bf16 v[16:19], v[194:197], v[234:237], v[16:19]
	v_mfma_f32_16x16x32_bf16 v[4:7], v[144:147], v[242:245], v[4:7]
	v_mfma_f32_16x16x32_bf16 v[0:3], v[194:197], v[242:245], v[0:3]
	v_mfma_f32_16x16x32_bf16 v[52:55], v[148:151], v[222:225], v[52:55]
	v_mfma_f32_16x16x32_bf16 v[48:51], v[202:205], v[222:225], v[48:51]
	v_mfma_f32_16x16x32_bf16 v[36:39], v[148:151], v[230:233], v[36:39]
	v_mfma_f32_16x16x32_bf16 v[32:35], v[202:205], v[230:233], v[32:35]
	s_cmpk_gt_u32 s44, 0x55
	s_mov_b32 s44, s22
	v_mfma_f32_16x16x32_bf16 v[20:23], v[148:151], v[238:241], v[20:23]
	v_mfma_f32_16x16x32_bf16 v[16:19], v[202:205], v[238:241], v[16:19]
	v_mfma_f32_16x16x32_bf16 v[4:7], v[148:151], v[246:249], v[4:7]
	s_setprio 2
	s_barrier
	v_mfma_f32_16x16x32_bf16 v[0:3], v[202:205], v[246:249], v[0:3]
	s_setprio 0
	s_cbranch_scc1 .LBB0_1028
